# write-through (sc1) 16-byte stores for GEMM1 P/G, UP H and prologue weight outputs: shorter L2 writeback at the grid barriers
# speedup vs baseline: 1.0217x; 1.0133x over previous
; __device__ __forceinline__ unsigned cvtpk(float lo, float hi) { f32x2_t v = {lo, hi}; f16x2_t b = __builtin_convertvector(v, f16x2_t); return __builtin_bit_cast(unsigned, b); }
; #define LAS __attribute__((address_space(3)))
; __device__ __forceinline__ void p0_transpose_item(const float* W, const float* gain, int K, int N, bf16* WT, LAS float* scr, int item, int lane) {
;     ...
;     for (int i = 0; i < 32; ++i) scr[(2 * i + (lane >> 5)) * 33 + (lane & 31)] = tv[i];
;     asm volatile("s_waitcnt lgkmcnt(0)" ::: "memory");
;     const int c = lane & 7;
; #pragma unroll
;     for (int j = 0; j < 4; ++j) { const int n = (lane >> 3) + 8 * j; const LAS float* s = scr + (8 * c) * 33 + n;
;         u32x4 o; o.x = cvtpk(s[0 * 33], s[1 * 33]); o.y = cvtpk(s[2 * 33], s[3 * 33]); o.z = cvtpk(s[4 * 33], s[5 * 33]); o.w = cvtpk(s[6 * 33], s[7 * 33]);
;         *(u32x4*)(WT + (size_t)(n0 + n) * K + k0 + 8 * c) = o; }
.LBB0_8:
	s_waitcnt vmcnt(30)
	ds_write2_b32 v40, v6, v7 offset1:66
	s_waitcnt vmcnt(28)
	ds_write2_b32 v40, v8, v9 offset0:132 offset1:198
	s_waitcnt vmcnt(26)
	ds_write2_b32 v46, v10, v11 offset0:8 offset1:74
	s_waitcnt vmcnt(24)
	ds_write2_b32 v46, v12, v13 offset0:140 offset1:206
	s_waitcnt vmcnt(22)
	ds_write2_b32 v47, v14, v15 offset0:16 offset1:82
	s_waitcnt vmcnt(20)
	ds_write2_b32 v47, v16, v17 offset0:148 offset1:214
	s_waitcnt vmcnt(18)
	ds_write2_b32 v48, v18, v19 offset0:24 offset1:90
	s_waitcnt vmcnt(16)
	ds_write2_b32 v48, v20, v21 offset0:156 offset1:222
	s_waitcnt vmcnt(14)
	ds_write2_b32 v49, v22, v23 offset0:32 offset1:98
	s_waitcnt vmcnt(12)
	ds_write2_b32 v49, v24, v25 offset0:164 offset1:230
	s_waitcnt vmcnt(10)
	ds_write2_b32 v50, v26, v27 offset0:40 offset1:106
	s_waitcnt vmcnt(8)
	ds_write2_b32 v50, v28, v29 offset0:172 offset1:238
	s_waitcnt vmcnt(6)
	ds_write2_b32 v51, v30, v31 offset0:48 offset1:114
	s_waitcnt vmcnt(4)
	ds_write2_b32 v51, v32, v33 offset0:180 offset1:246
	s_waitcnt vmcnt(2)
	ds_write2_b32 v52, v36, v37 offset0:56 offset1:122
	s_waitcnt vmcnt(0)
	ds_write2_b32 v52, v34, v35 offset0:188 offset1:254
	s_waitcnt lgkmcnt(0)
	s_ashr_i32 s39, s38, 31
	ds_read2_b32 v[10:11], v42 offset0:33 offset1:41
	ds_read2_b32 v[12:13], v42 offset1:8
	ds_read2_b32 v[14:15], v42 offset0:66 offset1:74
	ds_read2_b32 v[16:17], v42 offset0:99 offset1:107
	ds_read2_b32 v[18:19], v42 offset0:132 offset1:140
	ds_read2_b32 v[20:21], v42 offset0:165 offset1:173
	ds_read2_b32 v[22:23], v42 offset0:198 offset1:206
	ds_read2_b32 v[24:25], v42 offset0:231 offset1:239
	s_lshl_b64 s[30:31], s[38:39], 1
	s_add_u32 s30, s93, s30
	v_or_b32_e32 v28, s34, v41
	s_addc_u32 s31, s94, s31
	v_mov_b32_e32 v5, v3
	v_ashrrev_i32_e32 v29, 31, v28
	v_lshl_add_u64 v[26:27], s[30:31], 0, v[4:5]
	v_lshlrev_b64 v[28:29], 11, v[28:29]
	s_waitcnt lgkmcnt(6)
	v_cvt_pk_f16_f32 v6, v12, v10
	s_waitcnt lgkmcnt(4)
	v_cvt_pk_f16_f32 v7, v14, v16
	s_waitcnt lgkmcnt(2)
	v_cvt_pk_f16_f32 v8, v18, v20
	s_waitcnt lgkmcnt(0)
	v_cvt_pk_f16_f32 v9, v22, v24
	v_lshl_add_u64 v[28:29], v[26:27], 0, v[28:29]
	v_or_b32_e32 v10, s34, v43
	global_store_dwordx4 v[28:29], v[6:9], off sc1
	s_nop 1
	v_cvt_pk_f16_f32 v6, v13, v11
	v_ashrrev_i32_e32 v11, 31, v10
	v_cvt_pk_f16_f32 v7, v15, v17
	v_cvt_pk_f16_f32 v8, v19, v21
	v_cvt_pk_f16_f32 v9, v23, v25
	v_lshlrev_b64 v[10:11], 11, v[10:11]
	ds_read2_b32 v[12:13], v42 offset0:49 offset1:57
	ds_read2_b32 v[14:15], v42 offset0:16 offset1:24
	ds_read2_b32 v[16:17], v42 offset0:82 offset1:90
	ds_read2_b32 v[18:19], v42 offset0:115 offset1:123
	ds_read2_b32 v[20:21], v42 offset0:148 offset1:156
	ds_read2_b32 v[22:23], v42 offset0:181 offset1:189
	ds_read2_b32 v[24:25], v42 offset0:214 offset1:222
	ds_read2_b32 v[28:29], v42 offset0:247 offset1:255
	v_lshl_add_u64 v[10:11], v[26:27], 0, v[10:11]
	global_store_dwordx4 v[10:11], v[6:9], off sc1
	v_or_b32_e32 v10, s34, v44
	v_ashrrev_i32_e32 v11, 31, v10
	v_lshlrev_b64 v[10:11], 11, v[10:11]
	s_waitcnt lgkmcnt(6)
	v_cvt_pk_f16_f32 v6, v14, v12
	s_waitcnt lgkmcnt(4)
	v_cvt_pk_f16_f32 v7, v16, v18
	s_waitcnt lgkmcnt(2)
	v_cvt_pk_f16_f32 v8, v20, v22
	s_waitcnt lgkmcnt(0)
	v_cvt_pk_f16_f32 v9, v24, v28
	v_lshl_add_u64 v[10:11], v[26:27], 0, v[10:11]
	global_store_dwordx4 v[10:11], v[6:9], off sc1
	v_or_b32_e32 v10, s34, v45
	v_ashrrev_i32_e32 v11, 31, v10
	v_lshlrev_b64 v[10:11], 11, v[10:11]
	v_cvt_pk_f16_f32 v6, v15, v13
	v_cvt_pk_f16_f32 v7, v17, v19
	v_cvt_pk_f16_f32 v8, v21, v23
	v_cvt_pk_f16_f32 v9, v25, v29
	v_lshl_add_u64 v[10:11], v[26:27], 0, v[10:11]
	global_store_dwordx4 v[10:11], v[6:9], off sc1
	s_waitcnt lgkmcnt(0)

; #define LAS __attribute__((address_space(3)))
; __device__ __forceinline__ void p0_transpose_item(const float* W, const float* gain, int K, int N, bf16* WT, LAS float* scr, int item, int lane) {
;     const int nblk = N / 32, kb = item / nblk, nb = item % nblk, k0 = 64 * kb, n0 = 32 * nb;
;     float tv[32];
; #pragma unroll
;     for (int i = 0; i < 32; ++i) { const int kk = 2 * i + (lane >> 5); tv[i] = W[(size_t)(k0 + kk) * N + n0 + (lane & 31)]; }
; __device__ __forceinline__ void p0_prologue(const Frame& F, const Ptrs& A) {
;     ...
;     for (int it = gw; it < 2 * I_LAYER; it += NGW) {
;         const int l = it / I_LAYER; int r = it - l * I_LAYER;
;         unsigned char* wl = A.ws + WS_W + (size_t)l * W_LAYER;
;         if (r < I_IN) { p0_transpose_item(A.w_in + (size_t)l * DM * DIN, A.mix_norm + l * DM, DM, DIN, (bf16*)(wl + W_IN), scr, r, F.lane); continue; } r -= I_IN;
;         if (r < I_A) { p0_transpose_item(A.w_a + (size_t)l * 512 * DM, nullptr, 512, DM, (bf16*)(wl + W_A), scr, r, F.lane); continue; } r -= I_A;
;         if (r < I_B) { p0_transpose_item(A.w_b + (size_t)l * DM * DM, nullptr, DM, DM, (bf16*)(wl + W_B), scr, r, F.lane); continue; } r -= I_B;
;         if (r < I_O) { p0_transpose_item(A.w_o + (size_t)l * DM * DM, nullptr, DM, DM, (bf16*)(wl + W_O), scr, r, F.lane); continue; } r -= I_O;
;         if (r < I_UP) { p0_transpose_item(A.w_up + (size_t)l * DM * DFF, A.ffn_norm + l * DM, DM, DFF, (bf16*)(wl + W_UP), scr, r, F.lane); continue; } r -= I_UP;
;         p0_transpose_item(A.w_down + (size_t)l * DFF * DM, nullptr, DFF, DM, (bf16*)(wl + W_DN), scr, r, F.lane);
.LBB0_10:
	s_mul_hi_i32 s6, s92, 0x66666667
	s_lshr_b32 s30, s6, 31
	s_ashr_i32 s6, s6, 12
	s_add_i32 s30, s6, s30
	s_mul_i32 s6, s30, 0xffffd800
	s_add_i32 s38, s92, s6
	s_ashr_i32 s31, s30, 31
	s_mul_i32 s34, s30, 0x2800000
	s_mul_hi_i32 s6, s30, 0x2800000
	s_add_u32 s93, s42, s34
	s_addc_u32 s94, s43, s6
	s_cmpk_gt_i32 s38, 0x12ff
	s_mov_b64 s[34:35], -1
	s_cbranch_scc0 .LBB0_30
	s_cmpk_gt_u32 s38, 0x13ff
	s_cbranch_scc0 .LBB0_27
	s_cmpk_gt_u32 s38, 0x15ff
	s_cbranch_scc0 .LBB0_24
	s_cmpk_gt_u32 s38, 0x17ff
	s_cbranch_scc0 .LBB0_21
	s_cmpk_gt_u32 s38, 0x1fff
	s_cbranch_scc0 .LBB0_16
	s_lshl_b64 s[34:35], s[30:31], 24
	s_add_u32 s39, s56, s34
	s_mul_i32 s6, s30, 0xffffb000
	s_addc_u32 s35, s57, s35
	s_add_i32 s6, s46, s6
	s_andn2_b32 s6, s6, 63
	s_addk_i32 s6, 0xc000
	s_and_b32 s34, s44, 0x3e0
	v_or_b32_e32 v6, s6, v1
	s_lshl_b32 s95, s34, 2
	s_add_u32 s96, s39, s95
	v_or_b32_e32 v12, 2, v6
	v_or_b32_e32 v14, 4, v6
	v_or_b32_e32 v16, 6, v6
	v_or_b32_e32 v18, 8, v6
	v_or_b32_e32 v20, 10, v6
	v_or_b32_e32 v22, 12, v6
	v_or_b32_e32 v24, 14, v6
	s_addc_u32 s97, s35, 0
	v_ashrrev_i32_e32 v7, 31, v6
	v_ashrrev_i32_e32 v13, 31, v12
	v_ashrrev_i32_e32 v15, 31, v14
	v_ashrrev_i32_e32 v17, 31, v16
	v_ashrrev_i32_e32 v19, 31, v18
	v_ashrrev_i32_e32 v21, 31, v20
	v_ashrrev_i32_e32 v23, 31, v22
	v_ashrrev_i32_e32 v25, 31, v24
	v_lshl_add_u64 v[8:9], s[96:97], 0, v[2:3]
	v_lshlrev_b64 v[10:11], 12, v[6:7]
	v_lshlrev_b64 v[12:13], 12, v[12:13]
	v_lshlrev_b64 v[14:15], 12, v[14:15]
	v_lshlrev_b64 v[16:17], 12, v[16:17]
	v_lshlrev_b64 v[18:19], 12, v[18:19]
	v_lshlrev_b64 v[20:21], 12, v[20:21]
	v_lshlrev_b64 v[22:23], 12, v[22:23]
	v_lshlrev_b64 v[24:25], 12, v[24:25]
	v_lshl_add_u64 v[10:11], v[8:9], 0, v[10:11]
	v_lshl_add_u64 v[12:13], v[8:9], 0, v[12:13]
	v_lshl_add_u64 v[14:15], v[8:9], 0, v[14:15]
	v_lshl_add_u64 v[16:17], v[8:9], 0, v[16:17]
	v_lshl_add_u64 v[18:19], v[8:9], 0, v[18:19]
	v_lshl_add_u64 v[20:21], v[8:9], 0, v[20:21]
	v_lshl_add_u64 v[22:23], v[8:9], 0, v[22:23]
	v_lshl_add_u64 v[24:25], v[8:9], 0, v[24:25]
	global_load_dword v5, v[10:11], off
	global_load_dword v26, v[12:13], off
	global_load_dword v27, v[14:15], off
	global_load_dword v28, v[16:17], off
	global_load_dword v29, v[18:19], off
	global_load_dword v30, v[20:21], off
	global_load_dword v31, v[22:23], off
	global_load_dword v32, v[24:25], off
	v_or_b32_e32 v10, 16, v6
	v_or_b32_e32 v12, 18, v6
	v_or_b32_e32 v14, 20, v6
	v_or_b32_e32 v16, 22, v6
	v_or_b32_e32 v18, 24, v6
	v_or_b32_e32 v20, 26, v6
	v_or_b32_e32 v22, 28, v6
	v_or_b32_e32 v24, 30, v6
	v_ashrrev_i32_e32 v11, 31, v10
	v_ashrrev_i32_e32 v13, 31, v12
	v_ashrrev_i32_e32 v15, 31, v14
	v_ashrrev_i32_e32 v17, 31, v16
	v_ashrrev_i32_e32 v19, 31, v18
	v_ashrrev_i32_e32 v21, 31, v20
	v_ashrrev_i32_e32 v23, 31, v22
	v_ashrrev_i32_e32 v25, 31, v24
	v_lshlrev_b64 v[10:11], 12, v[10:11]
	v_lshlrev_b64 v[12:13], 12, v[12:13]
	v_lshlrev_b64 v[14:15], 12, v[14:15]
	v_lshlrev_b64 v[16:17], 12, v[16:17]
	v_lshlrev_b64 v[18:19], 12, v[18:19]
	v_lshlrev_b64 v[20:21], 12, v[20:21]
	v_lshlrev_b64 v[22:23], 12, v[22:23]
	v_lshlrev_b64 v[24:25], 12, v[24:25]
	v_lshl_add_u64 v[10:11], v[8:9], 0, v[10:11]
	v_lshl_add_u64 v[12:13], v[8:9], 0, v[12:13]
	v_lshl_add_u64 v[14:15], v[8:9], 0, v[14:15]
	v_lshl_add_u64 v[16:17], v[8:9], 0, v[16:17]
	v_lshl_add_u64 v[18:19], v[8:9], 0, v[18:19]
	v_lshl_add_u64 v[20:21], v[8:9], 0, v[20:21]
	v_lshl_add_u64 v[22:23], v[8:9], 0, v[22:23]
	v_lshl_add_u64 v[24:25], v[8:9], 0, v[24:25]
	global_load_dword v33, v[10:11], off
	global_load_dword v34, v[12:13], off
	global_load_dword v35, v[14:15], off
	global_load_dword v36, v[16:17], off
	global_load_dword v37, v[18:19], off
	global_load_dword v38, v[20:21], off
	global_load_dword v39, v[22:23], off
	global_load_dword v53, v[24:25], off
	v_or_b32_e32 v10, 32, v6
	v_or_b32_e32 v12, 34, v6
	v_or_b32_e32 v14, 36, v6
	v_or_b32_e32 v16, 38, v6
	v_or_b32_e32 v18, 40, v6
	v_or_b32_e32 v20, 42, v6
	v_or_b32_e32 v22, 44, v6
	v_or_b32_e32 v24, 46, v6
	v_ashrrev_i32_e32 v11, 31, v10
	v_ashrrev_i32_e32 v13, 31, v12
	v_ashrrev_i32_e32 v15, 31, v14
	v_ashrrev_i32_e32 v17, 31, v16
	v_ashrrev_i32_e32 v19, 31, v18
	v_ashrrev_i32_e32 v21, 31, v20
	v_ashrrev_i32_e32 v23, 31, v22
	v_ashrrev_i32_e32 v25, 31, v24
	v_lshlrev_b64 v[10:11], 12, v[10:11]
	v_lshlrev_b64 v[12:13], 12, v[12:13]
	v_lshlrev_b64 v[14:15], 12, v[14:15]
	v_lshlrev_b64 v[16:17], 12, v[16:17]
	v_lshlrev_b64 v[18:19], 12, v[18:19]
	v_lshlrev_b64 v[20:21], 12, v[20:21]
	v_lshlrev_b64 v[22:23], 12, v[22:23]
	v_lshlrev_b64 v[24:25], 12, v[24:25]
	v_lshl_add_u64 v[10:11], v[8:9], 0, v[10:11]
	v_lshl_add_u64 v[12:13], v[8:9], 0, v[12:13]
	v_lshl_add_u64 v[14:15], v[8:9], 0, v[14:15]
	v_lshl_add_u64 v[16:17], v[8:9], 0, v[16:17]
	v_lshl_add_u64 v[18:19], v[8:9], 0, v[18:19]
	v_lshl_add_u64 v[20:21], v[8:9], 0, v[20:21]
	v_lshl_add_u64 v[22:23], v[8:9], 0, v[22:23]
	v_lshl_add_u64 v[24:25], v[8:9], 0, v[24:25]
	global_load_dword v54, v[10:11], off
	global_load_dword v55, v[12:13], off
	global_load_dword v56, v[14:15], off
	global_load_dword v57, v[16:17], off
	global_load_dword v58, v[18:19], off
	global_load_dword v59, v[20:21], off
	global_load_dword v60, v[22:23], off
	s_nop 0
	global_load_dword v24, v[24:25], off
	v_or_b32_e32 v10, 48, v6
	v_or_b32_e32 v12, 50, v6
	v_or_b32_e32 v14, 52, v6
	v_or_b32_e32 v16, 54, v6
	v_or_b32_e32 v18, 56, v6
	v_or_b32_e32 v20, 58, v6
	v_or_b32_e32 v22, 60, v6
	v_or_b32_e32 v6, 62, v6
	v_ashrrev_i32_e32 v11, 31, v10
	v_ashrrev_i32_e32 v13, 31, v12
	v_ashrrev_i32_e32 v15, 31, v14
	v_ashrrev_i32_e32 v7, 31, v6
	v_lshlrev_b64 v[10:11], 12, v[10:11]
	v_lshlrev_b64 v[12:13], 12, v[12:13]
	v_lshlrev_b64 v[14:15], 12, v[14:15]
	v_ashrrev_i32_e32 v17, 31, v16
	v_ashrrev_i32_e32 v19, 31, v18
	v_ashrrev_i32_e32 v21, 31, v20
	v_ashrrev_i32_e32 v23, 31, v22
	v_lshlrev_b64 v[6:7], 12, v[6:7]
	v_lshl_add_u64 v[10:11], v[8:9], 0, v[10:11]
	v_lshl_add_u64 v[12:13], v[8:9], 0, v[12:13]
	v_lshl_add_u64 v[14:15], v[8:9], 0, v[14:15]
	v_lshlrev_b64 v[16:17], 12, v[16:17]
	v_lshlrev_b64 v[18:19], 12, v[18:19]
	v_lshlrev_b64 v[20:21], 12, v[20:21]
	v_lshlrev_b64 v[22:23], 12, v[22:23]
	v_lshl_add_u64 v[6:7], v[8:9], 0, v[6:7]
	v_lshl_add_u64 v[16:17], v[8:9], 0, v[16:17]
	v_lshl_add_u64 v[18:19], v[8:9], 0, v[18:19]
	v_lshl_add_u64 v[20:21], v[8:9], 0, v[20:21]
	v_lshl_add_u64 v[22:23], v[8:9], 0, v[22:23]
	global_load_dword v8, v[10:11], off
	global_load_dword v9, v[12:13], off
	s_nop 0
	global_load_dword v10, v[14:15], off
	global_load_dword v11, v[16:17], off
	global_load_dword v12, v[18:19], off
	global_load_dword v13, v[20:21], off
	s_nop 0
	global_load_dword v14, v[22:23], off
	s_nop 0
	global_load_dword v6, v[6:7], off
	s_waitcnt vmcnt(30)
; __device__ __forceinline__ unsigned cvtpk(float lo, float hi) { f32x2_t v = {lo, hi}; f16x2_t b = __builtin_convertvector(v, f16x2_t); return __builtin_bit_cast(unsigned, b); }
; #define LAS __attribute__((address_space(3)))
; __device__ __forceinline__ void p0_transpose_item(const float* W, const float* gain, int K, int N, bf16* WT, LAS float* scr, int item, int lane) {
;     ...
;     for (int i = 0; i < 32; ++i) scr[(2 * i + (lane >> 5)) * 33 + (lane & 31)] = tv[i];
;     asm volatile("s_waitcnt lgkmcnt(0)" ::: "memory");
;     const int c = lane & 7;
; #pragma unroll
;     for (int j = 0; j < 4; ++j) { const int n = (lane >> 3) + 8 * j; const LAS float* s = scr + (8 * c) * 33 + n;
;         u32x4 o; o.x = cvtpk(s[0 * 33], s[1 * 33]); o.y = cvtpk(s[2 * 33], s[3 * 33]); o.z = cvtpk(s[4 * 33], s[5 * 33]); o.w = cvtpk(s[6 * 33], s[7 * 33]);
;         *(u32x4*)(WT + (size_t)(n0 + n) * K + k0 + 8 * c) = o; }
	ds_write2_b32 v40, v5, v26 offset1:66
	s_waitcnt vmcnt(28)
	ds_write2_b32 v40, v27, v28 offset0:132 offset1:198
	s_waitcnt vmcnt(26)
	ds_write2_b32 v46, v29, v30 offset0:8 offset1:74
	s_waitcnt vmcnt(24)
	ds_write2_b32 v46, v31, v32 offset0:140 offset1:206
	s_waitcnt vmcnt(22)
	ds_write2_b32 v47, v33, v34 offset0:16 offset1:82
	s_waitcnt vmcnt(20)
	ds_write2_b32 v47, v35, v36 offset0:148 offset1:214
	s_waitcnt vmcnt(18)
	ds_write2_b32 v48, v37, v38 offset0:24 offset1:90
	s_waitcnt vmcnt(16)
	ds_write2_b32 v48, v39, v53 offset0:156 offset1:222
	s_waitcnt vmcnt(14)
	ds_write2_b32 v49, v54, v55 offset0:32 offset1:98
	s_waitcnt vmcnt(12)
	ds_write2_b32 v49, v56, v57 offset0:164 offset1:230
	s_waitcnt vmcnt(10)
	ds_write2_b32 v50, v58, v59 offset0:40 offset1:106
	s_waitcnt vmcnt(8)
	ds_write2_b32 v50, v60, v24 offset0:172 offset1:238
	s_waitcnt vmcnt(6)
	ds_write2_b32 v51, v8, v9 offset0:48 offset1:114
	s_waitcnt vmcnt(4)
	ds_write2_b32 v51, v10, v11 offset0:180 offset1:246
	s_waitcnt vmcnt(2)
	ds_write2_b32 v52, v12, v13 offset0:56 offset1:122
	s_waitcnt vmcnt(0)
	ds_write2_b32 v52, v14, v6 offset0:188 offset1:254
	s_waitcnt lgkmcnt(0)
	s_lshl_b64 s[96:97], s[6:7], 1
	ds_read2_b32 v[10:11], v42 offset0:33 offset1:41
	ds_read2_b32 v[12:13], v42 offset1:8
	ds_read2_b32 v[14:15], v42 offset0:66 offset1:74
	ds_read2_b32 v[16:17], v42 offset0:99 offset1:107
	ds_read2_b32 v[18:19], v42 offset0:132 offset1:140
	ds_read2_b32 v[20:21], v42 offset0:165 offset1:173
	ds_read2_b32 v[22:23], v42 offset0:198 offset1:206
	ds_read2_b32 v[24:25], v42 offset0:231 offset1:239
	s_add_u32 s96, s93, s96
	s_addc_u32 s97, s94, s97
	v_mov_b32_e32 v5, v3
	v_lshl_add_u64 v[6:7], s[96:97], 0, v[4:5]
	s_mov_b64 s[96:97], 0x2000000
	v_or_b32_e32 v5, s34, v41
	v_lshl_add_u64 v[26:27], v[6:7], 0, s[96:97]
	v_lshlrev_b32_e32 v28, 13, v5
	v_mov_b32_e32 v29, v3
	s_waitcnt lgkmcnt(6)
	v_cvt_pk_f16_f32 v6, v12, v10
	s_waitcnt lgkmcnt(4)
	v_cvt_pk_f16_f32 v7, v14, v16
	s_waitcnt lgkmcnt(2)
	v_cvt_pk_f16_f32 v8, v18, v20
	s_waitcnt lgkmcnt(0)
	v_cvt_pk_f16_f32 v9, v22, v24
	v_lshl_add_u64 v[28:29], v[26:27], 0, v[28:29]
	global_store_dwordx4 v[28:29], v[6:9], off sc1
	v_or_b32_e32 v5, s34, v43
	v_lshlrev_b32_e32 v10, 13, v5
	v_cvt_pk_f16_f32 v6, v13, v11
	v_cvt_pk_f16_f32 v7, v15, v17
	v_cvt_pk_f16_f32 v8, v19, v21
	v_cvt_pk_f16_f32 v9, v23, v25
	ds_read2_b32 v[12:13], v42 offset0:49 offset1:57
	ds_read2_b32 v[14:15], v42 offset0:16 offset1:24
	ds_read2_b32 v[16:17], v42 offset0:82 offset1:90
	ds_read2_b32 v[18:19], v42 offset0:115 offset1:123
	ds_read2_b32 v[20:21], v42 offset0:148 offset1:156
	ds_read2_b32 v[22:23], v42 offset0:181 offset1:189
	ds_read2_b32 v[24:25], v42 offset0:214 offset1:222
	ds_read2_b32 v[28:29], v42 offset0:247 offset1:255
	v_mov_b32_e32 v11, v3
	v_lshl_add_u64 v[10:11], v[26:27], 0, v[10:11]
	v_or_b32_e32 v5, s34, v44
	global_store_dwordx4 v[10:11], v[6:9], off sc1
	v_lshlrev_b32_e32 v10, 13, v5
	v_mov_b32_e32 v11, v3
	s_waitcnt lgkmcnt(6)
	v_cvt_pk_f16_f32 v6, v14, v12
	s_waitcnt lgkmcnt(4)
	v_cvt_pk_f16_f32 v7, v16, v18
	s_waitcnt lgkmcnt(2)
	v_cvt_pk_f16_f32 v8, v20, v22
	s_waitcnt lgkmcnt(0)
	v_cvt_pk_f16_f32 v9, v24, v28
	v_lshl_add_u64 v[10:11], v[26:27], 0, v[10:11]
	v_or_b32_e32 v5, s34, v45
	global_store_dwordx4 v[10:11], v[6:9], off sc1
	v_lshlrev_b32_e32 v10, 13, v5
	v_mov_b32_e32 v11, v3
	v_cvt_pk_f16_f32 v6, v15, v13
	v_cvt_pk_f16_f32 v7, v17, v19
	v_cvt_pk_f16_f32 v8, v21, v23
	v_cvt_pk_f16_f32 v9, v25, v29
	v_lshl_add_u64 v[10:11], v[26:27], 0, v[10:11]
	global_store_dwordx4 v[10:11], v[6:9], off sc1
	s_waitcnt lgkmcnt(0)
	s_mov_b64 s[34:35], 0

; __device__ __forceinline__ unsigned cvtpk(float lo, float hi) { f32x2_t v = {lo, hi}; f16x2_t b = __builtin_convertvector(v, f16x2_t); return __builtin_bit_cast(unsigned, b); }
; #define LAS __attribute__((address_space(3)))
; __device__ __forceinline__ void p0_transpose_item(const float* W, const float* gain, int K, int N, bf16* WT, LAS float* scr, int item, int lane) {
;     ...
;     for (int i = 0; i < 32; ++i) scr[(2 * i + (lane >> 5)) * 33 + (lane & 31)] = tv[i];
;     asm volatile("s_waitcnt lgkmcnt(0)" ::: "memory");
;     const int c = lane & 7;
; #pragma unroll
;     for (int j = 0; j < 4; ++j) { const int n = (lane >> 3) + 8 * j; const LAS float* s = scr + (8 * c) * 33 + n;
;         u32x4 o; o.x = cvtpk(s[0 * 33], s[1 * 33]); o.y = cvtpk(s[2 * 33], s[3 * 33]); o.z = cvtpk(s[4 * 33], s[5 * 33]); o.w = cvtpk(s[6 * 33], s[7 * 33]);
;         *(u32x4*)(WT + (size_t)(n0 + n) * K + k0 + 8 * c) = o; }
.LBB0_19:
	s_waitcnt vmcnt(30)
	ds_write2_b32 v40, v6, v7 offset1:66
	s_waitcnt vmcnt(28)
	ds_write2_b32 v40, v8, v9 offset0:132 offset1:198
	s_waitcnt vmcnt(26)
	ds_write2_b32 v46, v10, v11 offset0:8 offset1:74
	s_waitcnt vmcnt(24)
	ds_write2_b32 v46, v12, v13 offset0:140 offset1:206
	s_waitcnt vmcnt(22)
	ds_write2_b32 v47, v14, v15 offset0:16 offset1:82
	s_waitcnt vmcnt(20)
	ds_write2_b32 v47, v16, v17 offset0:148 offset1:214
	s_waitcnt vmcnt(18)
	ds_write2_b32 v48, v18, v19 offset0:24 offset1:90
	s_waitcnt vmcnt(16)
	ds_write2_b32 v48, v20, v21 offset0:156 offset1:222
	s_waitcnt vmcnt(14)
	ds_write2_b32 v49, v22, v23 offset0:32 offset1:98
	s_waitcnt vmcnt(12)
	ds_write2_b32 v49, v24, v25 offset0:164 offset1:230
	s_waitcnt vmcnt(10)
	ds_write2_b32 v50, v26, v27 offset0:40 offset1:106
	s_waitcnt vmcnt(8)
	ds_write2_b32 v50, v28, v29 offset0:172 offset1:238
	s_waitcnt vmcnt(6)
	ds_write2_b32 v51, v30, v31 offset0:48 offset1:114
	s_waitcnt vmcnt(4)
	ds_write2_b32 v51, v32, v33 offset0:180 offset1:246
	s_waitcnt vmcnt(2)
	ds_write2_b32 v52, v36, v37 offset0:56 offset1:122
	s_waitcnt vmcnt(0)
	ds_write2_b32 v52, v34, v35 offset0:188 offset1:254
	s_waitcnt lgkmcnt(0)
	s_lshl_b32 s34, s34, 1
	ds_read2_b32 v[10:11], v42 offset0:33 offset1:41
	ds_read2_b32 v[12:13], v42 offset1:8
	ds_read2_b32 v[14:15], v42 offset0:66 offset1:74
	ds_read2_b32 v[16:17], v42 offset0:99 offset1:107
	ds_read2_b32 v[18:19], v42 offset0:132 offset1:140
	ds_read2_b32 v[20:21], v42 offset0:165 offset1:173
	ds_read2_b32 v[22:23], v42 offset0:198 offset1:206
	ds_read2_b32 v[24:25], v42 offset0:231 offset1:239
	s_add_u32 s34, s93, s34
	s_addc_u32 s35, s94, 0
	v_mov_b32_e32 v5, v3
	v_lshl_add_u64 v[6:7], s[34:35], 0, v[4:5]
	s_mov_b64 s[34:35], 0x1800000
	v_or_b32_e32 v5, s6, v41
	v_lshl_add_u64 v[26:27], v[6:7], 0, s[34:35]
	v_lshlrev_b32_e32 v28, 11, v5
	v_mov_b32_e32 v29, v3
	s_waitcnt lgkmcnt(6)
	v_cvt_pk_f16_f32 v6, v12, v10
	s_waitcnt lgkmcnt(4)
	v_cvt_pk_f16_f32 v7, v14, v16
	s_waitcnt lgkmcnt(2)
	v_cvt_pk_f16_f32 v8, v18, v20
	s_waitcnt lgkmcnt(0)
	v_cvt_pk_f16_f32 v9, v22, v24
	v_lshl_add_u64 v[28:29], v[26:27], 0, v[28:29]
	global_store_dwordx4 v[28:29], v[6:9], off sc1
	v_or_b32_e32 v5, s6, v43
	v_lshlrev_b32_e32 v10, 11, v5
	v_cvt_pk_f16_f32 v6, v13, v11
	v_cvt_pk_f16_f32 v7, v15, v17
	v_cvt_pk_f16_f32 v8, v19, v21
	v_cvt_pk_f16_f32 v9, v23, v25
	ds_read2_b32 v[12:13], v42 offset0:49 offset1:57
	ds_read2_b32 v[14:15], v42 offset0:16 offset1:24
	ds_read2_b32 v[16:17], v42 offset0:82 offset1:90
	ds_read2_b32 v[18:19], v42 offset0:115 offset1:123
	ds_read2_b32 v[20:21], v42 offset0:148 offset1:156
	ds_read2_b32 v[22:23], v42 offset0:181 offset1:189
	ds_read2_b32 v[24:25], v42 offset0:214 offset1:222
	ds_read2_b32 v[28:29], v42 offset0:247 offset1:255
	v_mov_b32_e32 v11, v3
	v_lshl_add_u64 v[10:11], v[26:27], 0, v[10:11]
	v_or_b32_e32 v5, s6, v44
	global_store_dwordx4 v[10:11], v[6:9], off sc1
	v_lshlrev_b32_e32 v10, 11, v5
	v_mov_b32_e32 v11, v3
	s_waitcnt lgkmcnt(6)
	v_cvt_pk_f16_f32 v6, v14, v12
	s_waitcnt lgkmcnt(4)
	v_cvt_pk_f16_f32 v7, v16, v18
	s_waitcnt lgkmcnt(2)
	v_cvt_pk_f16_f32 v8, v20, v22
	s_waitcnt lgkmcnt(0)
	v_cvt_pk_f16_f32 v9, v24, v28
	v_lshl_add_u64 v[10:11], v[26:27], 0, v[10:11]
	v_or_b32_e32 v5, s6, v45
	global_store_dwordx4 v[10:11], v[6:9], off sc1
	v_lshlrev_b32_e32 v10, 11, v5
	v_mov_b32_e32 v11, v3
	v_cvt_pk_f16_f32 v6, v15, v13
	v_cvt_pk_f16_f32 v7, v17, v19
	v_cvt_pk_f16_f32 v8, v21, v23
	v_cvt_pk_f16_f32 v9, v25, v29
	v_lshl_add_u64 v[10:11], v[26:27], 0, v[10:11]
	global_store_dwordx4 v[10:11], v[6:9], off sc1
	s_waitcnt lgkmcnt(0)

; #define LAS __attribute__((address_space(3)))
; __device__ __forceinline__ void p0_transpose_item(const float* W, const float* gain, int K, int N, bf16* WT, LAS float* scr, int item, int lane) {
;     const int nblk = N / 32, kb = item / nblk, nb = item % nblk, k0 = 64 * kb, n0 = 32 * nb;
;     float tv[32];
; #pragma unroll
;     for (int i = 0; i < 32; ++i) { const int kk = 2 * i + (lane >> 5); tv[i] = W[(size_t)(k0 + kk) * N + n0 + (lane & 31)]; }
; __device__ __forceinline__ void p0_prologue(const Frame& F, const Ptrs& A) {
;     ...
;     for (int it = gw; it < 2 * I_LAYER; it += NGW) {
;         const int l = it / I_LAYER; int r = it - l * I_LAYER;
;         unsigned char* wl = A.ws + WS_W + (size_t)l * W_LAYER;
;         if (r < I_IN) { p0_transpose_item(A.w_in + (size_t)l * DM * DIN, A.mix_norm + l * DM, DM, DIN, (bf16*)(wl + W_IN), scr, r, F.lane); continue; } r -= I_IN;
;         if (r < I_A) { p0_transpose_item(A.w_a + (size_t)l * 512 * DM, nullptr, 512, DM, (bf16*)(wl + W_A), scr, r, F.lane); continue; } r -= I_A;
;         if (r < I_B) { p0_transpose_item(A.w_b + (size_t)l * DM * DM, nullptr, DM, DM, (bf16*)(wl + W_B), scr, r, F.lane); continue; } r -= I_B;
;         if (r < I_O) { p0_transpose_item(A.w_o + (size_t)l * DM * DM, nullptr, DM, DM, (bf16*)(wl + W_O), scr, r, F.lane); continue; } r -= I_O;
.LBB0_21:
	s_andn2_b64 vcc, exec, s[34:35]
	s_cbranch_vccnz .LBB0_23
	s_lshl_b64 s[34:35], s[30:31], 22
	s_add_u32 s39, s18, s34
	s_mul_i32 s6, s30, 0xffffb000
	s_addc_u32 s35, s19, s35
	s_add_i32 s6, s46, s6
	s_add_i32 s6, s6, 0x1d400
	s_and_b32 s34, s6, 0x1ffc0
	s_and_b32 s6, s44, 0x3e0
	s_lshl_b32 s95, s6, 2
	s_add_u32 s96, s39, s95
	v_or_b32_e32 v5, s34, v1
	s_addc_u32 s97, s35, 0
	v_lshl_add_u64 v[6:7], s[96:97], 0, v[2:3]
	v_lshlrev_b32_e32 v8, 12, v5
	v_mov_b32_e32 v9, v3
	v_lshl_add_u64 v[6:7], v[6:7], 0, v[8:9]
	v_add_co_u32_e32 v8, vcc, s55, v6
	s_lshl_b32 s34, s34, 1
	s_nop 0
	v_addc_co_u32_e32 v9, vcc, 0, v7, vcc
	v_add_co_u32_e32 v10, vcc, s68, v6
	s_add_u32 s34, s93, s34
	s_nop 0
	v_addc_co_u32_e32 v11, vcc, 0, v7, vcc
	v_add_co_u32_e32 v12, vcc, s69, v6
	s_addc_u32 s35, s94, 0
	s_nop 0
	v_addc_co_u32_e32 v13, vcc, 0, v7, vcc
	v_add_co_u32_e32 v14, vcc, s48, v6
	s_nop 1
	v_addc_co_u32_e32 v15, vcc, 0, v7, vcc
	v_add_co_u32_e32 v16, vcc, s70, v6
	s_nop 1
	v_addc_co_u32_e32 v17, vcc, 0, v7, vcc
	v_add_co_u32_e32 v18, vcc, s71, v6
	s_nop 1
	v_addc_co_u32_e32 v19, vcc, 0, v7, vcc
	v_add_co_u32_e32 v20, vcc, s72, v6
	s_nop 1
	v_addc_co_u32_e32 v21, vcc, 0, v7, vcc
	global_load_dword v5, v[6:7], off
	global_load_dword v24, v[8:9], off
	global_load_dword v25, v[10:11], off
	global_load_dword v26, v[12:13], off
	global_load_dword v27, v[14:15], off
	global_load_dword v28, v[16:17], off
	global_load_dword v29, v[18:19], off
	global_load_dword v30, v[20:21], off
	v_add_co_u32_e32 v8, vcc, s49, v6
	s_nop 1
	v_addc_co_u32_e32 v9, vcc, 0, v7, vcc
	v_add_co_u32_e32 v10, vcc, s73, v6
	s_nop 1
	v_addc_co_u32_e32 v11, vcc, 0, v7, vcc
	v_add_co_u32_e32 v12, vcc, s74, v6
	s_nop 1
	v_addc_co_u32_e32 v13, vcc, 0, v7, vcc
	v_add_co_u32_e32 v14, vcc, s75, v6
	s_nop 1
	v_addc_co_u32_e32 v15, vcc, 0, v7, vcc
	v_add_co_u32_e32 v16, vcc, s2, v6
	s_nop 1
	v_addc_co_u32_e32 v17, vcc, 0, v7, vcc
	v_add_co_u32_e32 v18, vcc, s76, v6
	s_nop 1
	v_addc_co_u32_e32 v19, vcc, 0, v7, vcc
	v_add_co_u32_e32 v20, vcc, s77, v6
	s_nop 1
	v_addc_co_u32_e32 v21, vcc, 0, v7, vcc
	v_add_co_u32_e32 v22, vcc, s78, v6
	s_nop 1
	v_addc_co_u32_e32 v23, vcc, 0, v7, vcc
	global_load_dword v31, v[8:9], off
	global_load_dword v32, v[10:11], off
	global_load_dword v33, v[12:13], off
	global_load_dword v34, v[14:15], off
	global_load_dword v35, v[16:17], off
	global_load_dword v36, v[18:19], off
	global_load_dword v37, v[20:21], off
	global_load_dword v38, v[22:23], off
	v_add_co_u32_e32 v8, vcc, s3, v6
	s_nop 1
	v_addc_co_u32_e32 v9, vcc, 0, v7, vcc
	v_add_co_u32_e32 v10, vcc, s79, v6
	s_nop 1
	v_addc_co_u32_e32 v11, vcc, 0, v7, vcc
	v_add_co_u32_e32 v12, vcc, s80, v6
	s_nop 1
	v_addc_co_u32_e32 v13, vcc, 0, v7, vcc
	v_add_co_u32_e32 v14, vcc, s81, v6
	s_nop 1
	v_addc_co_u32_e32 v15, vcc, 0, v7, vcc
	v_add_co_u32_e32 v16, vcc, s52, v6
	s_nop 1
	v_addc_co_u32_e32 v17, vcc, 0, v7, vcc
	v_add_co_u32_e32 v18, vcc, s82, v6
	s_nop 1
	v_addc_co_u32_e32 v19, vcc, 0, v7, vcc
	v_add_co_u32_e32 v20, vcc, s83, v6
	s_nop 1
	v_addc_co_u32_e32 v21, vcc, 0, v7, vcc
	v_add_co_u32_e32 v22, vcc, s84, v6
	s_nop 1
	v_addc_co_u32_e32 v23, vcc, 0, v7, vcc
	global_load_dword v39, v[8:9], off
	global_load_dword v53, v[10:11], off
	global_load_dword v54, v[12:13], off
	global_load_dword v55, v[14:15], off
	global_load_dword v56, v[16:17], off
	global_load_dword v57, v[18:19], off
	global_load_dword v58, v[20:21], off
	s_nop 0
	global_load_dword v22, v[22:23], off
	v_add_co_u32_e32 v8, vcc, s53, v6
	s_nop 1
	v_addc_co_u32_e32 v9, vcc, 0, v7, vcc
	v_add_co_u32_e32 v10, vcc, s85, v6
	s_nop 1
	v_addc_co_u32_e32 v11, vcc, 0, v7, vcc
	v_add_co_u32_e32 v12, vcc, s86, v6
	s_nop 1
	v_addc_co_u32_e32 v13, vcc, 0, v7, vcc
	v_add_co_u32_e32 v14, vcc, s87, v6
	s_nop 1
	v_addc_co_u32_e32 v15, vcc, 0, v7, vcc
	v_add_co_u32_e32 v16, vcc, s54, v6
	s_nop 1
	v_addc_co_u32_e32 v17, vcc, 0, v7, vcc
	v_add_co_u32_e32 v18, vcc, s88, v6
	s_nop 1
	v_addc_co_u32_e32 v19, vcc, 0, v7, vcc
	v_add_co_u32_e32 v20, vcc, s89, v6
	s_nop 1
	v_addc_co_u32_e32 v21, vcc, 0, v7, vcc
	v_add_co_u32_e32 v6, vcc, s90, v6
	s_nop 1
	v_addc_co_u32_e32 v7, vcc, 0, v7, vcc
	global_load_dword v8, v[8:9], off
	s_nop 0
	global_load_dword v9, v[10:11], off
	s_nop 0
	global_load_dword v10, v[12:13], off
	global_load_dword v11, v[14:15], off
	s_nop 0
	global_load_dword v12, v[16:17], off
	global_load_dword v13, v[18:19], off
	global_load_dword v14, v[20:21], off
	s_nop 0
	global_load_dword v6, v[6:7], off
	s_waitcnt vmcnt(30)
; __device__ __forceinline__ unsigned cvtpk(float lo, float hi) { f32x2_t v = {lo, hi}; f16x2_t b = __builtin_convertvector(v, f16x2_t); return __builtin_bit_cast(unsigned, b); }
; #define LAS __attribute__((address_space(3)))
; __device__ __forceinline__ void p0_transpose_item(const float* W, const float* gain, int K, int N, bf16* WT, LAS float* scr, int item, int lane) {
;     ...
;     for (int i = 0; i < 32; ++i) scr[(2 * i + (lane >> 5)) * 33 + (lane & 31)] = tv[i];
;     asm volatile("s_waitcnt lgkmcnt(0)" ::: "memory");
;     const int c = lane & 7;
; #pragma unroll
;     for (int j = 0; j < 4; ++j) { const int n = (lane >> 3) + 8 * j; const LAS float* s = scr + (8 * c) * 33 + n;
;         u32x4 o; o.x = cvtpk(s[0 * 33], s[1 * 33]); o.y = cvtpk(s[2 * 33], s[3 * 33]); o.z = cvtpk(s[4 * 33], s[5 * 33]); o.w = cvtpk(s[6 * 33], s[7 * 33]);
;         *(u32x4*)(WT + (size_t)(n0 + n) * K + k0 + 8 * c) = o; }
	ds_write2_b32 v40, v5, v24 offset1:66
	s_waitcnt vmcnt(28)
	ds_write2_b32 v40, v25, v26 offset0:132 offset1:198
	s_waitcnt vmcnt(26)
	ds_write2_b32 v46, v27, v28 offset0:8 offset1:74
	s_waitcnt vmcnt(24)
	ds_write2_b32 v46, v29, v30 offset0:140 offset1:206
	s_waitcnt vmcnt(22)
	ds_write2_b32 v47, v31, v32 offset0:16 offset1:82
	s_waitcnt vmcnt(20)
	ds_write2_b32 v47, v33, v34 offset0:148 offset1:214
	s_waitcnt vmcnt(18)
	ds_write2_b32 v48, v35, v36 offset0:24 offset1:90
	s_waitcnt vmcnt(16)
	ds_write2_b32 v48, v37, v38 offset0:156 offset1:222
	s_waitcnt vmcnt(14)
	ds_write2_b32 v49, v39, v53 offset0:32 offset1:98
	s_waitcnt vmcnt(12)
	ds_write2_b32 v49, v54, v55 offset0:164 offset1:230
	s_waitcnt vmcnt(10)
	ds_write2_b32 v50, v56, v57 offset0:40 offset1:106
	s_waitcnt vmcnt(8)
	ds_write2_b32 v50, v58, v22 offset0:172 offset1:238
	s_waitcnt vmcnt(6)
	ds_write2_b32 v51, v8, v9 offset0:48 offset1:114
	s_waitcnt vmcnt(4)
	ds_write2_b32 v51, v10, v11 offset0:180 offset1:246
	s_waitcnt vmcnt(2)
	ds_write2_b32 v52, v12, v13 offset0:56 offset1:122
	s_waitcnt vmcnt(0)
	ds_write2_b32 v52, v14, v6 offset0:188 offset1:254
	s_waitcnt lgkmcnt(0)
	ds_read2_b32 v[10:11], v42 offset0:33 offset1:41
	ds_read2_b32 v[12:13], v42 offset1:8
	ds_read2_b32 v[14:15], v42 offset0:66 offset1:74
	ds_read2_b32 v[16:17], v42 offset0:99 offset1:107
	ds_read2_b32 v[18:19], v42 offset0:132 offset1:140
	ds_read2_b32 v[20:21], v42 offset0:165 offset1:173
	ds_read2_b32 v[22:23], v42 offset0:198 offset1:206
	ds_read2_b32 v[24:25], v42 offset0:231 offset1:239
	v_mov_b32_e32 v5, v3
	v_lshl_add_u64 v[6:7], s[34:35], 0, v[4:5]
	s_mov_b64 s[34:35], 0x1600000
	v_or_b32_e32 v5, s6, v41
	v_lshl_add_u64 v[26:27], v[6:7], 0, s[34:35]
	v_lshlrev_b32_e32 v28, 11, v5
	v_mov_b32_e32 v29, v3
	s_waitcnt lgkmcnt(6)
	v_cvt_pk_f16_f32 v6, v12, v10
	s_waitcnt lgkmcnt(4)
	v_cvt_pk_f16_f32 v7, v14, v16
	s_waitcnt lgkmcnt(2)
	v_cvt_pk_f16_f32 v8, v18, v20
	s_waitcnt lgkmcnt(0)
	v_cvt_pk_f16_f32 v9, v22, v24
	v_lshl_add_u64 v[28:29], v[26:27], 0, v[28:29]
	global_store_dwordx4 v[28:29], v[6:9], off sc1
	v_or_b32_e32 v5, s6, v43
	v_lshlrev_b32_e32 v10, 11, v5
	v_cvt_pk_f16_f32 v6, v13, v11
	v_cvt_pk_f16_f32 v7, v15, v17
	v_cvt_pk_f16_f32 v8, v19, v21
	v_cvt_pk_f16_f32 v9, v23, v25
	ds_read2_b32 v[12:13], v42 offset0:49 offset1:57
	ds_read2_b32 v[14:15], v42 offset0:16 offset1:24
	ds_read2_b32 v[16:17], v42 offset0:82 offset1:90
	ds_read2_b32 v[18:19], v42 offset0:115 offset1:123
	ds_read2_b32 v[20:21], v42 offset0:148 offset1:156
	ds_read2_b32 v[22:23], v42 offset0:181 offset1:189
	ds_read2_b32 v[24:25], v42 offset0:214 offset1:222
	ds_read2_b32 v[28:29], v42 offset0:247 offset1:255
	v_mov_b32_e32 v11, v3
	v_lshl_add_u64 v[10:11], v[26:27], 0, v[10:11]
	v_or_b32_e32 v5, s6, v44
	global_store_dwordx4 v[10:11], v[6:9], off sc1
	v_lshlrev_b32_e32 v10, 11, v5
	v_mov_b32_e32 v11, v3
	s_waitcnt lgkmcnt(6)
	v_cvt_pk_f16_f32 v6, v14, v12
	s_waitcnt lgkmcnt(4)
	v_cvt_pk_f16_f32 v7, v16, v18
	s_waitcnt lgkmcnt(2)
	v_cvt_pk_f16_f32 v8, v20, v22
	s_waitcnt lgkmcnt(0)
	v_cvt_pk_f16_f32 v9, v24, v28
	v_lshl_add_u64 v[10:11], v[26:27], 0, v[10:11]
	v_or_b32_e32 v5, s6, v45
	global_store_dwordx4 v[10:11], v[6:9], off sc1
	v_lshlrev_b32_e32 v10, 11, v5
	v_mov_b32_e32 v11, v3
	v_cvt_pk_f16_f32 v6, v15, v13
	v_cvt_pk_f16_f32 v7, v17, v19
	v_cvt_pk_f16_f32 v8, v21, v23
	v_cvt_pk_f16_f32 v9, v25, v29
	v_lshl_add_u64 v[10:11], v[26:27], 0, v[10:11]
	global_store_dwordx4 v[10:11], v[6:9], off sc1
	s_waitcnt lgkmcnt(0)

; #define LAS __attribute__((address_space(3)))
; __device__ __forceinline__ void p0_transpose_item(const float* W, const float* gain, int K, int N, bf16* WT, LAS float* scr, int item, int lane) {
;     const int nblk = N / 32, kb = item / nblk, nb = item % nblk, k0 = 64 * kb, n0 = 32 * nb;
;     float tv[32];
; #pragma unroll
;     for (int i = 0; i < 32; ++i) { const int kk = 2 * i + (lane >> 5); tv[i] = W[(size_t)(k0 + kk) * N + n0 + (lane & 31)]; }
; __device__ __forceinline__ void p0_prologue(const Frame& F, const Ptrs& A) {
;     ...
;     for (int it = gw; it < 2 * I_LAYER; it += NGW) {
;         const int l = it / I_LAYER; int r = it - l * I_LAYER;
;         unsigned char* wl = A.ws + WS_W + (size_t)l * W_LAYER;
;         if (r < I_IN) { p0_transpose_item(A.w_in + (size_t)l * DM * DIN, A.mix_norm + l * DM, DM, DIN, (bf16*)(wl + W_IN), scr, r, F.lane); continue; } r -= I_IN;
;         if (r < I_A) { p0_transpose_item(A.w_a + (size_t)l * 512 * DM, nullptr, 512, DM, (bf16*)(wl + W_A), scr, r, F.lane); continue; } r -= I_A;
;         if (r < I_B) { p0_transpose_item(A.w_b + (size_t)l * DM * DM, nullptr, DM, DM, (bf16*)(wl + W_B), scr, r, F.lane); continue; } r -= I_B;
.LBB0_24:
	s_andn2_b64 vcc, exec, s[34:35]
	s_cbranch_vccnz .LBB0_26
	s_lshl_b64 s[34:35], s[30:31], 22
	s_add_u32 s39, s16, s34
	s_mul_i32 s6, s30, 0xffffb000
	s_addc_u32 s35, s17, s35
	s_add_i32 s6, s46, s6
	s_add_i32 s6, s6, 0x1d800
	s_and_b32 s34, s6, 0x1ffc0
	s_and_b32 s6, s44, 0x3e0
	s_lshl_b32 s95, s6, 2
	s_add_u32 s96, s39, s95
	v_or_b32_e32 v5, s34, v1
	s_addc_u32 s97, s35, 0
	v_lshl_add_u64 v[6:7], s[96:97], 0, v[2:3]
	v_lshlrev_b32_e32 v8, 12, v5
	v_mov_b32_e32 v9, v3
	v_lshl_add_u64 v[6:7], v[6:7], 0, v[8:9]
	v_add_co_u32_e32 v8, vcc, s55, v6
	s_lshl_b32 s34, s34, 1
	s_nop 0
	v_addc_co_u32_e32 v9, vcc, 0, v7, vcc
	v_add_co_u32_e32 v10, vcc, s68, v6
	s_add_u32 s34, s93, s34
	s_nop 0
	v_addc_co_u32_e32 v11, vcc, 0, v7, vcc
	v_add_co_u32_e32 v12, vcc, s69, v6
	s_addc_u32 s35, s94, 0
	s_nop 0
	v_addc_co_u32_e32 v13, vcc, 0, v7, vcc
	v_add_co_u32_e32 v14, vcc, s48, v6
	s_nop 1
	v_addc_co_u32_e32 v15, vcc, 0, v7, vcc
	v_add_co_u32_e32 v16, vcc, s70, v6
	s_nop 1
	v_addc_co_u32_e32 v17, vcc, 0, v7, vcc
	v_add_co_u32_e32 v18, vcc, s71, v6
	s_nop 1
	v_addc_co_u32_e32 v19, vcc, 0, v7, vcc
	v_add_co_u32_e32 v20, vcc, s72, v6
	s_nop 1
	v_addc_co_u32_e32 v21, vcc, 0, v7, vcc
	global_load_dword v5, v[6:7], off
	global_load_dword v24, v[8:9], off
	global_load_dword v25, v[10:11], off
	global_load_dword v26, v[12:13], off
	global_load_dword v27, v[14:15], off
	global_load_dword v28, v[16:17], off
	global_load_dword v29, v[18:19], off
	global_load_dword v30, v[20:21], off
	v_add_co_u32_e32 v8, vcc, s49, v6
	s_nop 1
	v_addc_co_u32_e32 v9, vcc, 0, v7, vcc
	v_add_co_u32_e32 v10, vcc, s73, v6
	s_nop 1
	v_addc_co_u32_e32 v11, vcc, 0, v7, vcc
	v_add_co_u32_e32 v12, vcc, s74, v6
	s_nop 1
	v_addc_co_u32_e32 v13, vcc, 0, v7, vcc
	v_add_co_u32_e32 v14, vcc, s75, v6
	s_nop 1
	v_addc_co_u32_e32 v15, vcc, 0, v7, vcc
	v_add_co_u32_e32 v16, vcc, s2, v6
	s_nop 1
	v_addc_co_u32_e32 v17, vcc, 0, v7, vcc
	v_add_co_u32_e32 v18, vcc, s76, v6
	s_nop 1
	v_addc_co_u32_e32 v19, vcc, 0, v7, vcc
	v_add_co_u32_e32 v20, vcc, s77, v6
	s_nop 1
	v_addc_co_u32_e32 v21, vcc, 0, v7, vcc
	v_add_co_u32_e32 v22, vcc, s78, v6
	s_nop 1
	v_addc_co_u32_e32 v23, vcc, 0, v7, vcc
	global_load_dword v31, v[8:9], off
	global_load_dword v32, v[10:11], off
	global_load_dword v33, v[12:13], off
	global_load_dword v34, v[14:15], off
	global_load_dword v35, v[16:17], off
	global_load_dword v36, v[18:19], off
	global_load_dword v37, v[20:21], off
	global_load_dword v38, v[22:23], off
	v_add_co_u32_e32 v8, vcc, s3, v6
	s_nop 1
	v_addc_co_u32_e32 v9, vcc, 0, v7, vcc
	v_add_co_u32_e32 v10, vcc, s79, v6
	s_nop 1
	v_addc_co_u32_e32 v11, vcc, 0, v7, vcc
	v_add_co_u32_e32 v12, vcc, s80, v6
	s_nop 1
	v_addc_co_u32_e32 v13, vcc, 0, v7, vcc
	v_add_co_u32_e32 v14, vcc, s81, v6
	s_nop 1
	v_addc_co_u32_e32 v15, vcc, 0, v7, vcc
	v_add_co_u32_e32 v16, vcc, s52, v6
	s_nop 1
	v_addc_co_u32_e32 v17, vcc, 0, v7, vcc
	v_add_co_u32_e32 v18, vcc, s82, v6
	s_nop 1
	v_addc_co_u32_e32 v19, vcc, 0, v7, vcc
	v_add_co_u32_e32 v20, vcc, s83, v6
	s_nop 1
	v_addc_co_u32_e32 v21, vcc, 0, v7, vcc
	v_add_co_u32_e32 v22, vcc, s84, v6
	s_nop 1
	v_addc_co_u32_e32 v23, vcc, 0, v7, vcc
	global_load_dword v39, v[8:9], off
	global_load_dword v53, v[10:11], off
	global_load_dword v54, v[12:13], off
	global_load_dword v55, v[14:15], off
	global_load_dword v56, v[16:17], off
	global_load_dword v57, v[18:19], off
	global_load_dword v58, v[20:21], off
	s_nop 0
	global_load_dword v22, v[22:23], off
	v_add_co_u32_e32 v8, vcc, s53, v6
	s_nop 1
	v_addc_co_u32_e32 v9, vcc, 0, v7, vcc
	v_add_co_u32_e32 v10, vcc, s85, v6
	s_nop 1
	v_addc_co_u32_e32 v11, vcc, 0, v7, vcc
	v_add_co_u32_e32 v12, vcc, s86, v6
	s_nop 1
	v_addc_co_u32_e32 v13, vcc, 0, v7, vcc
	v_add_co_u32_e32 v14, vcc, s87, v6
	s_nop 1
	v_addc_co_u32_e32 v15, vcc, 0, v7, vcc
	v_add_co_u32_e32 v16, vcc, s54, v6
	s_nop 1
	v_addc_co_u32_e32 v17, vcc, 0, v7, vcc
	v_add_co_u32_e32 v18, vcc, s88, v6
	s_nop 1
	v_addc_co_u32_e32 v19, vcc, 0, v7, vcc
	v_add_co_u32_e32 v20, vcc, s89, v6
	s_nop 1
	v_addc_co_u32_e32 v21, vcc, 0, v7, vcc
	v_add_co_u32_e32 v6, vcc, s90, v6
	s_nop 1
	v_addc_co_u32_e32 v7, vcc, 0, v7, vcc
	global_load_dword v8, v[8:9], off
	s_nop 0
	global_load_dword v9, v[10:11], off
	s_nop 0
	global_load_dword v10, v[12:13], off
	global_load_dword v11, v[14:15], off
	s_nop 0
	global_load_dword v12, v[16:17], off
	global_load_dword v13, v[18:19], off
	global_load_dword v14, v[20:21], off
	s_nop 0
	global_load_dword v6, v[6:7], off
	s_waitcnt vmcnt(30)
; __device__ __forceinline__ unsigned cvtpk(float lo, float hi) { f32x2_t v = {lo, hi}; f16x2_t b = __builtin_convertvector(v, f16x2_t); return __builtin_bit_cast(unsigned, b); }
; #define LAS __attribute__((address_space(3)))
; __device__ __forceinline__ void p0_transpose_item(const float* W, const float* gain, int K, int N, bf16* WT, LAS float* scr, int item, int lane) {
;     ...
;     for (int i = 0; i < 32; ++i) scr[(2 * i + (lane >> 5)) * 33 + (lane & 31)] = tv[i];
;     asm volatile("s_waitcnt lgkmcnt(0)" ::: "memory");
;     const int c = lane & 7;
; #pragma unroll
;     for (int j = 0; j < 4; ++j) { const int n = (lane >> 3) + 8 * j; const LAS float* s = scr + (8 * c) * 33 + n;
;         u32x4 o; o.x = cvtpk(s[0 * 33], s[1 * 33]); o.y = cvtpk(s[2 * 33], s[3 * 33]); o.z = cvtpk(s[4 * 33], s[5 * 33]); o.w = cvtpk(s[6 * 33], s[7 * 33]);
;         *(u32x4*)(WT + (size_t)(n0 + n) * K + k0 + 8 * c) = o; }
	ds_write2_b32 v40, v5, v24 offset1:66
	s_waitcnt vmcnt(28)
	ds_write2_b32 v40, v25, v26 offset0:132 offset1:198
	s_waitcnt vmcnt(26)
	ds_write2_b32 v46, v27, v28 offset0:8 offset1:74
	s_waitcnt vmcnt(24)
	ds_write2_b32 v46, v29, v30 offset0:140 offset1:206
	s_waitcnt vmcnt(22)
	ds_write2_b32 v47, v31, v32 offset0:16 offset1:82
	s_waitcnt vmcnt(20)
	ds_write2_b32 v47, v33, v34 offset0:148 offset1:214
	s_waitcnt vmcnt(18)
	ds_write2_b32 v48, v35, v36 offset0:24 offset1:90
	s_waitcnt vmcnt(16)
	ds_write2_b32 v48, v37, v38 offset0:156 offset1:222
	s_waitcnt vmcnt(14)
	ds_write2_b32 v49, v39, v53 offset0:32 offset1:98
	s_waitcnt vmcnt(12)
	ds_write2_b32 v49, v54, v55 offset0:164 offset1:230
	s_waitcnt vmcnt(10)
	ds_write2_b32 v50, v56, v57 offset0:40 offset1:106
	s_waitcnt vmcnt(8)
	ds_write2_b32 v50, v58, v22 offset0:172 offset1:238
	s_waitcnt vmcnt(6)
	ds_write2_b32 v51, v8, v9 offset0:48 offset1:114
	s_waitcnt vmcnt(4)
	ds_write2_b32 v51, v10, v11 offset0:180 offset1:246
	s_waitcnt vmcnt(2)
	ds_write2_b32 v52, v12, v13 offset0:56 offset1:122
	s_waitcnt vmcnt(0)
	ds_write2_b32 v52, v14, v6 offset0:188 offset1:254
	s_waitcnt lgkmcnt(0)
	ds_read2_b32 v[10:11], v42 offset0:33 offset1:41
	ds_read2_b32 v[12:13], v42 offset1:8
	ds_read2_b32 v[14:15], v42 offset0:66 offset1:74
	ds_read2_b32 v[16:17], v42 offset0:99 offset1:107
	ds_read2_b32 v[18:19], v42 offset0:132 offset1:140
	ds_read2_b32 v[20:21], v42 offset0:165 offset1:173
	ds_read2_b32 v[22:23], v42 offset0:198 offset1:206
	ds_read2_b32 v[24:25], v42 offset0:231 offset1:239
	v_mov_b32_e32 v5, v3
	v_lshl_add_u64 v[6:7], s[34:35], 0, v[4:5]
	v_or_b32_e32 v5, s6, v41
	v_lshl_add_u64 v[26:27], v[6:7], 0, s[0:1]
	v_lshlrev_b32_e32 v28, 11, v5
	v_mov_b32_e32 v29, v3
	s_waitcnt lgkmcnt(6)
	v_cvt_pk_f16_f32 v6, v12, v10
	s_waitcnt lgkmcnt(4)
	v_cvt_pk_f16_f32 v7, v14, v16
	s_waitcnt lgkmcnt(2)
	v_cvt_pk_f16_f32 v8, v18, v20
	s_waitcnt lgkmcnt(0)
	v_cvt_pk_f16_f32 v9, v22, v24
	v_lshl_add_u64 v[28:29], v[26:27], 0, v[28:29]
	global_store_dwordx4 v[28:29], v[6:9], off sc1
	v_or_b32_e32 v5, s6, v43
	v_lshlrev_b32_e32 v10, 11, v5
	v_cvt_pk_f16_f32 v6, v13, v11
	v_cvt_pk_f16_f32 v7, v15, v17
	v_cvt_pk_f16_f32 v8, v19, v21
	v_cvt_pk_f16_f32 v9, v23, v25
	ds_read2_b32 v[12:13], v42 offset0:49 offset1:57
	ds_read2_b32 v[14:15], v42 offset0:16 offset1:24
	ds_read2_b32 v[16:17], v42 offset0:82 offset1:90
	ds_read2_b32 v[18:19], v42 offset0:115 offset1:123
	ds_read2_b32 v[20:21], v42 offset0:148 offset1:156
	ds_read2_b32 v[22:23], v42 offset0:181 offset1:189
	ds_read2_b32 v[24:25], v42 offset0:214 offset1:222
	ds_read2_b32 v[28:29], v42 offset0:247 offset1:255
	v_mov_b32_e32 v11, v3
	v_lshl_add_u64 v[10:11], v[26:27], 0, v[10:11]
	v_or_b32_e32 v5, s6, v44
	global_store_dwordx4 v[10:11], v[6:9], off sc1
	v_lshlrev_b32_e32 v10, 11, v5
	v_mov_b32_e32 v11, v3
	s_waitcnt lgkmcnt(6)
	v_cvt_pk_f16_f32 v6, v14, v12
	s_waitcnt lgkmcnt(4)
	v_cvt_pk_f16_f32 v7, v16, v18
	s_waitcnt lgkmcnt(2)
	v_cvt_pk_f16_f32 v8, v20, v22
	s_waitcnt lgkmcnt(0)
	v_cvt_pk_f16_f32 v9, v24, v28
	v_lshl_add_u64 v[10:11], v[26:27], 0, v[10:11]
	v_or_b32_e32 v5, s6, v45
	global_store_dwordx4 v[10:11], v[6:9], off sc1
	v_lshlrev_b32_e32 v10, 11, v5
	v_mov_b32_e32 v11, v3
	v_cvt_pk_f16_f32 v6, v15, v13
	v_cvt_pk_f16_f32 v7, v17, v19
	v_cvt_pk_f16_f32 v8, v21, v23
	v_cvt_pk_f16_f32 v9, v25, v29
	v_lshl_add_u64 v[10:11], v[26:27], 0, v[10:11]
	global_store_dwordx4 v[10:11], v[6:9], off sc1
	s_waitcnt lgkmcnt(0)

; #define LAS __attribute__((address_space(3)))
; __device__ __forceinline__ void p0_transpose_item(const float* W, const float* gain, int K, int N, bf16* WT, LAS float* scr, int item, int lane) {
;     const int nblk = N / 32, kb = item / nblk, nb = item % nblk, k0 = 64 * kb, n0 = 32 * nb;
;     float tv[32];
; #pragma unroll
;     for (int i = 0; i < 32; ++i) { const int kk = 2 * i + (lane >> 5); tv[i] = W[(size_t)(k0 + kk) * N + n0 + (lane & 31)]; }
; __device__ __forceinline__ void p0_prologue(const Frame& F, const Ptrs& A) {
;     ...
;     for (int it = gw; it < 2 * I_LAYER; it += NGW) {
;         const int l = it / I_LAYER; int r = it - l * I_LAYER;
;         unsigned char* wl = A.ws + WS_W + (size_t)l * W_LAYER;
;         if (r < I_IN) { p0_transpose_item(A.w_in + (size_t)l * DM * DIN, A.mix_norm + l * DM, DM, DIN, (bf16*)(wl + W_IN), scr, r, F.lane); continue; } r -= I_IN;
;         if (r < I_A) { p0_transpose_item(A.w_a + (size_t)l * 512 * DM, nullptr, 512, DM, (bf16*)(wl + W_A), scr, r, F.lane); continue; } r -= I_A;
.LBB0_27:
	s_andn2_b64 vcc, exec, s[34:35]
	s_cbranch_vccnz .LBB0_29
	s_lshl_b64 s[34:35], s[30:31], 21
	s_add_u32 s34, s14, s34
	s_addc_u32 s35, s15, s35
	s_and_b32 s6, s44, 0x3e0
	s_and_b32 s31, s46, 0x1c0
	s_lshl_b32 s39, s6, 2
	s_add_u32 s34, s34, s39
	v_or_b32_e32 v5, s31, v1
	s_addc_u32 s35, s35, 0
	v_lshl_add_u64 v[6:7], s[34:35], 0, v[2:3]
	v_lshlrev_b32_e32 v8, 12, v5
	v_mov_b32_e32 v9, v3
	v_lshl_add_u64 v[6:7], v[6:7], 0, v[8:9]
	v_add_co_u32_e32 v8, vcc, s55, v6
	s_lshl_b32 s31, s31, 1
	s_nop 0
	v_addc_co_u32_e32 v9, vcc, 0, v7, vcc
	v_add_co_u32_e32 v10, vcc, s68, v6
	s_add_u32 s34, s93, s31
	s_nop 0
	v_addc_co_u32_e32 v11, vcc, 0, v7, vcc
	v_add_co_u32_e32 v12, vcc, s69, v6
	s_addc_u32 s35, s94, 0
	s_nop 0
	v_addc_co_u32_e32 v13, vcc, 0, v7, vcc
	v_add_co_u32_e32 v14, vcc, s48, v6
	s_nop 1
	v_addc_co_u32_e32 v15, vcc, 0, v7, vcc
	v_add_co_u32_e32 v16, vcc, s70, v6
	s_nop 1
	v_addc_co_u32_e32 v17, vcc, 0, v7, vcc
	v_add_co_u32_e32 v18, vcc, s71, v6
	s_nop 1
	v_addc_co_u32_e32 v19, vcc, 0, v7, vcc
	v_add_co_u32_e32 v20, vcc, s72, v6
	s_nop 1
	v_addc_co_u32_e32 v21, vcc, 0, v7, vcc
	global_load_dword v5, v[6:7], off
	global_load_dword v24, v[8:9], off
	global_load_dword v25, v[10:11], off
	global_load_dword v26, v[12:13], off
	global_load_dword v27, v[14:15], off
	global_load_dword v28, v[16:17], off
	global_load_dword v29, v[18:19], off
	global_load_dword v30, v[20:21], off
	v_add_co_u32_e32 v8, vcc, s49, v6
	s_nop 1
	v_addc_co_u32_e32 v9, vcc, 0, v7, vcc
	v_add_co_u32_e32 v10, vcc, s73, v6
	s_nop 1
	v_addc_co_u32_e32 v11, vcc, 0, v7, vcc
	v_add_co_u32_e32 v12, vcc, s74, v6
	s_nop 1
	v_addc_co_u32_e32 v13, vcc, 0, v7, vcc
	v_add_co_u32_e32 v14, vcc, s75, v6
	s_nop 1
	v_addc_co_u32_e32 v15, vcc, 0, v7, vcc
	v_add_co_u32_e32 v16, vcc, s2, v6
	s_nop 1
	v_addc_co_u32_e32 v17, vcc, 0, v7, vcc
	v_add_co_u32_e32 v18, vcc, s76, v6
	s_nop 1
	v_addc_co_u32_e32 v19, vcc, 0, v7, vcc
	v_add_co_u32_e32 v20, vcc, s77, v6
	s_nop 1
	v_addc_co_u32_e32 v21, vcc, 0, v7, vcc
	v_add_co_u32_e32 v22, vcc, s78, v6
	s_nop 1
	v_addc_co_u32_e32 v23, vcc, 0, v7, vcc
	global_load_dword v31, v[8:9], off
	global_load_dword v32, v[10:11], off
	global_load_dword v33, v[12:13], off
	global_load_dword v34, v[14:15], off
	global_load_dword v35, v[16:17], off
	global_load_dword v36, v[18:19], off
	global_load_dword v37, v[20:21], off
	global_load_dword v38, v[22:23], off
	v_add_co_u32_e32 v8, vcc, s3, v6
	s_nop 1
	v_addc_co_u32_e32 v9, vcc, 0, v7, vcc
	v_add_co_u32_e32 v10, vcc, s79, v6
	s_nop 1
	v_addc_co_u32_e32 v11, vcc, 0, v7, vcc
	v_add_co_u32_e32 v12, vcc, s80, v6
	s_nop 1
	v_addc_co_u32_e32 v13, vcc, 0, v7, vcc
	v_add_co_u32_e32 v14, vcc, s81, v6
	s_nop 1
	v_addc_co_u32_e32 v15, vcc, 0, v7, vcc
	v_add_co_u32_e32 v16, vcc, s52, v6
	s_nop 1
	v_addc_co_u32_e32 v17, vcc, 0, v7, vcc
	v_add_co_u32_e32 v18, vcc, s82, v6
	s_nop 1
	v_addc_co_u32_e32 v19, vcc, 0, v7, vcc
	v_add_co_u32_e32 v20, vcc, s83, v6
	s_nop 1
	v_addc_co_u32_e32 v21, vcc, 0, v7, vcc
	v_add_co_u32_e32 v22, vcc, s84, v6
	s_nop 1
	v_addc_co_u32_e32 v23, vcc, 0, v7, vcc
	global_load_dword v39, v[8:9], off
	global_load_dword v53, v[10:11], off
	global_load_dword v54, v[12:13], off
	global_load_dword v55, v[14:15], off
	global_load_dword v56, v[16:17], off
	global_load_dword v57, v[18:19], off
	global_load_dword v58, v[20:21], off
	s_nop 0
	global_load_dword v22, v[22:23], off
	v_add_co_u32_e32 v8, vcc, s53, v6
	s_nop 1
	v_addc_co_u32_e32 v9, vcc, 0, v7, vcc
	v_add_co_u32_e32 v10, vcc, s85, v6
	s_nop 1
	v_addc_co_u32_e32 v11, vcc, 0, v7, vcc
	v_add_co_u32_e32 v12, vcc, s86, v6
	s_nop 1
	v_addc_co_u32_e32 v13, vcc, 0, v7, vcc
	v_add_co_u32_e32 v14, vcc, s87, v6
	s_nop 1
	v_addc_co_u32_e32 v15, vcc, 0, v7, vcc
	v_add_co_u32_e32 v16, vcc, s54, v6
	s_nop 1
	v_addc_co_u32_e32 v17, vcc, 0, v7, vcc
	v_add_co_u32_e32 v18, vcc, s88, v6
	s_nop 1
	v_addc_co_u32_e32 v19, vcc, 0, v7, vcc
	v_add_co_u32_e32 v20, vcc, s89, v6
	s_nop 1
	v_addc_co_u32_e32 v21, vcc, 0, v7, vcc
	v_add_co_u32_e32 v6, vcc, s90, v6
	s_nop 1
	v_addc_co_u32_e32 v7, vcc, 0, v7, vcc
	global_load_dword v8, v[8:9], off
	s_nop 0
	global_load_dword v9, v[10:11], off
	s_nop 0
	global_load_dword v10, v[12:13], off
	global_load_dword v11, v[14:15], off
	s_nop 0
	global_load_dword v12, v[16:17], off
	global_load_dword v13, v[18:19], off
	global_load_dword v14, v[20:21], off
	s_nop 0
	global_load_dword v6, v[6:7], off
	s_waitcnt vmcnt(30)
; __device__ __forceinline__ unsigned cvtpk(float lo, float hi) { f32x2_t v = {lo, hi}; f16x2_t b = __builtin_convertvector(v, f16x2_t); return __builtin_bit_cast(unsigned, b); }
; #define LAS __attribute__((address_space(3)))
; __device__ __forceinline__ void p0_transpose_item(const float* W, const float* gain, int K, int N, bf16* WT, LAS float* scr, int item, int lane) {
;     ...
;     for (int i = 0; i < 32; ++i) scr[(2 * i + (lane >> 5)) * 33 + (lane & 31)] = tv[i];
;     asm volatile("s_waitcnt lgkmcnt(0)" ::: "memory");
;     const int c = lane & 7;
; #pragma unroll
;     for (int j = 0; j < 4; ++j) { const int n = (lane >> 3) + 8 * j; const LAS float* s = scr + (8 * c) * 33 + n;
;         u32x4 o; o.x = cvtpk(s[0 * 33], s[1 * 33]); o.y = cvtpk(s[2 * 33], s[3 * 33]); o.z = cvtpk(s[4 * 33], s[5 * 33]); o.w = cvtpk(s[6 * 33], s[7 * 33]);
;         *(u32x4*)(WT + (size_t)(n0 + n) * K + k0 + 8 * c) = o; }
	ds_write2_b32 v40, v5, v24 offset1:66
	s_waitcnt vmcnt(28)
	ds_write2_b32 v40, v25, v26 offset0:132 offset1:198
	s_waitcnt vmcnt(26)
	ds_write2_b32 v46, v27, v28 offset0:8 offset1:74
	s_waitcnt vmcnt(24)
	ds_write2_b32 v46, v29, v30 offset0:140 offset1:206
	s_waitcnt vmcnt(22)
	ds_write2_b32 v47, v31, v32 offset0:16 offset1:82
	s_waitcnt vmcnt(20)
	ds_write2_b32 v47, v33, v34 offset0:148 offset1:214
	s_waitcnt vmcnt(18)
	ds_write2_b32 v48, v35, v36 offset0:24 offset1:90
	s_waitcnt vmcnt(16)
	ds_write2_b32 v48, v37, v38 offset0:156 offset1:222
	s_waitcnt vmcnt(14)
	ds_write2_b32 v49, v39, v53 offset0:32 offset1:98
	s_waitcnt vmcnt(12)
	ds_write2_b32 v49, v54, v55 offset0:164 offset1:230
	s_waitcnt vmcnt(10)
	ds_write2_b32 v50, v56, v57 offset0:40 offset1:106
	s_waitcnt vmcnt(8)
	ds_write2_b32 v50, v58, v22 offset0:172 offset1:238
	s_waitcnt vmcnt(6)
	ds_write2_b32 v51, v8, v9 offset0:48 offset1:114
	s_waitcnt vmcnt(4)
	ds_write2_b32 v51, v10, v11 offset0:180 offset1:246
	s_waitcnt vmcnt(2)
	ds_write2_b32 v52, v12, v13 offset0:56 offset1:122
	s_waitcnt vmcnt(0)
	ds_write2_b32 v52, v14, v6 offset0:188 offset1:254
	s_waitcnt lgkmcnt(0)
	ds_read2_b32 v[10:11], v42 offset0:33 offset1:41
	ds_read2_b32 v[12:13], v42 offset1:8
	ds_read2_b32 v[14:15], v42 offset0:66 offset1:74
	ds_read2_b32 v[16:17], v42 offset0:99 offset1:107
	ds_read2_b32 v[18:19], v42 offset0:132 offset1:140
	ds_read2_b32 v[20:21], v42 offset0:165 offset1:173
	ds_read2_b32 v[22:23], v42 offset0:198 offset1:206
	ds_read2_b32 v[24:25], v42 offset0:231 offset1:239
	v_mov_b32_e32 v5, v3
	v_lshl_add_u64 v[6:7], s[34:35], 0, v[4:5]
	v_or_b32_e32 v5, s6, v41
	v_lshl_add_u64 v[26:27], v[6:7], 0, s[28:29]
	v_lshlrev_b32_e32 v28, 10, v5
	v_mov_b32_e32 v29, v3
	s_waitcnt lgkmcnt(6)
	v_cvt_pk_f16_f32 v6, v12, v10
	s_waitcnt lgkmcnt(4)
	v_cvt_pk_f16_f32 v7, v14, v16
	s_waitcnt lgkmcnt(2)
	v_cvt_pk_f16_f32 v8, v18, v20
	s_waitcnt lgkmcnt(0)
	v_cvt_pk_f16_f32 v9, v22, v24
	v_lshl_add_u64 v[28:29], v[26:27], 0, v[28:29]
	global_store_dwordx4 v[28:29], v[6:9], off sc1
	v_or_b32_e32 v5, s6, v43
	v_lshlrev_b32_e32 v10, 10, v5
	v_cvt_pk_f16_f32 v6, v13, v11
	v_cvt_pk_f16_f32 v7, v15, v17
	v_cvt_pk_f16_f32 v8, v19, v21
	v_cvt_pk_f16_f32 v9, v23, v25
	ds_read2_b32 v[12:13], v42 offset0:49 offset1:57
	ds_read2_b32 v[14:15], v42 offset0:16 offset1:24
	ds_read2_b32 v[16:17], v42 offset0:82 offset1:90
	ds_read2_b32 v[18:19], v42 offset0:115 offset1:123
	ds_read2_b32 v[20:21], v42 offset0:148 offset1:156
	ds_read2_b32 v[22:23], v42 offset0:181 offset1:189
	ds_read2_b32 v[24:25], v42 offset0:214 offset1:222
	ds_read2_b32 v[28:29], v42 offset0:247 offset1:255
	v_mov_b32_e32 v11, v3
	v_lshl_add_u64 v[10:11], v[26:27], 0, v[10:11]
	v_or_b32_e32 v5, s6, v44
	global_store_dwordx4 v[10:11], v[6:9], off sc1
	v_lshlrev_b32_e32 v10, 10, v5
	v_mov_b32_e32 v11, v3
	s_waitcnt lgkmcnt(6)
	v_cvt_pk_f16_f32 v6, v14, v12
	s_waitcnt lgkmcnt(4)
	v_cvt_pk_f16_f32 v7, v16, v18
	s_waitcnt lgkmcnt(2)
	v_cvt_pk_f16_f32 v8, v20, v22
	s_waitcnt lgkmcnt(0)
	v_cvt_pk_f16_f32 v9, v24, v28
	v_lshl_add_u64 v[10:11], v[26:27], 0, v[10:11]
	v_or_b32_e32 v5, s6, v45
	global_store_dwordx4 v[10:11], v[6:9], off sc1
	v_lshlrev_b32_e32 v10, 10, v5
	v_mov_b32_e32 v11, v3
	v_cvt_pk_f16_f32 v6, v15, v13
	v_cvt_pk_f16_f32 v7, v17, v19
	v_cvt_pk_f16_f32 v8, v21, v23
	v_cvt_pk_f16_f32 v9, v25, v29
	v_lshl_add_u64 v[10:11], v[26:27], 0, v[10:11]
	global_store_dwordx4 v[10:11], v[6:9], off sc1
	s_waitcnt lgkmcnt(0)

; #define PG8_LAS __attribute__((address_space(3)))
; __device__ __forceinline__ unsigned cvtpk(float lo, float hi) { f32x2_t v = {lo, hi}; f16x2_t b = __builtin_convertvector(v, f16x2_t); return __builtin_bit_cast(unsigned, b); }
;     __device__ __forceinline__ void operator()(const f32x4 (&acc)[2][2][4][2], const Unit& u, int wr, int wc, int fr, int fq) const {
;     ...
;         float rs[2][4]; const PG8_LAS float* tb = rsl + (u.pm == pmA ? 0 : 256);
; #pragma unroll
;         for (int ai = 0; ai < 2; ++ai)
; #pragma unroll
;             for (int m = 0; m < 4; ++m) rs[ai][m] = tb[ai * HALF + wr * 64 + m * 16 + fr];
; #pragma unroll
;         for (int ai = 0; ai < 2; ++ai)
; #pragma unroll
;             for (int m = 0; m < 4; ++m) { const int row = row0 + ai * HALF + m * 16; bf16_t* rowp = H + (size_t)row * 4096 + col0;
; #pragma unroll
;                 for (int bj = 0; bj < 2; ++bj) { f32x4 v0 = acc[ai][bj][m][0] * rs[ai][m], v1 = acc[ai][bj][m][1] * rs[ai][m];
; #pragma unroll
;                     for (int e = 0; e < 4; ++e) { const float a = fmaxf(v0[e], 0.f), b = fmaxf(v1[e], 0.f); v0[e] = a * a; v1[e] = b * b; }
;                     u32x4 w; w.x = cvtpk(v0[0], v0[1]); w.y = cvtpk(v0[2], v0[3]); w.z = cvtpk(v1[0], v1[1]); w.w = cvtpk(v1[2], v1[3]);
;                     *(u32x4*)(rowp + bj * HALF) = w; } }
.LBB0_970:
	v_readlane_b32 s21, v255, 57
	s_cmp_eq_u32 s42, s21
	s_cselect_b32 s21, 0, 0x400
	v_add_u32_e32 v140, s21, v153
	v_lshl_add_u32 v148, s42, 8, v151
	ds_read2_b32 v[156:157], v140 offset1:16
	ds_read2_b32 v[146:147], v140 offset0:32 offset1:48
	ds_read2_b32 v[144:145], v140 offset0:128 offset1:144
	ds_read2_b32 v[142:143], v140 offset0:160 offset1:176
	v_lshl_or_b32 v140, s53, 8, v154
	v_ashrrev_i32_e32 v149, 31, v148
	v_ashrrev_i32_e32 v141, 31, v140
	v_lshlrev_b64 v[158:159], 13, v[148:149]
	s_waitcnt lgkmcnt(0)
	v_pk_mul_f32 v[122:123], v[122:123], v[156:157] op_sel_hi:[1,0]
	v_lshl_add_u64 v[158:159], s[74:75], 0, v[158:159]
	v_lshlrev_b64 v[160:161], 1, v[140:141]
	v_pk_mul_f32 v[128:129], v[128:129], v[156:157] op_sel_hi:[1,0]
	v_pk_mul_f32 v[126:127], v[126:127], v[156:157] op_sel_hi:[1,0]
	v_pk_mul_f32 v[124:125], v[124:125], v[156:157] op_sel_hi:[1,0]
	v_max_f32_e32 v122, 0, v122
	v_max_f32_e32 v123, 0, v123
	v_lshl_add_u64 v[140:141], v[158:159], 0, v[160:161]
	v_max_f32_e32 v126, 0, v126
	v_max_f32_e32 v127, 0, v127
	v_pk_mul_f32 v[158:159], v[122:123], v[122:123]
	v_max_f32_e32 v122, 0, v128
	v_max_f32_e32 v124, 0, v124
	v_max_f32_e32 v123, 0, v129
	v_max_f32_e32 v125, 0, v125
	v_pk_mul_f32 v[126:127], v[126:127], v[126:127]
	v_pk_mul_f32 v[128:129], v[122:123], v[122:123]
	v_pk_mul_f32 v[172:173], v[124:125], v[124:125]
	v_pk_mul_f32 v[114:115], v[114:115], v[156:157] op_sel_hi:[1,0]
	v_cvt_pk_f16_f32 v122, v126, v127
	v_cvt_pk_f16_f32 v123, v128, v129
	v_cvt_pk_f16_f32 v124, v158, v159
	v_cvt_pk_f16_f32 v125, v172, v173
	v_pk_mul_f32 v[120:121], v[120:121], v[156:157] op_sel_hi:[1,0]
	v_pk_mul_f32 v[118:119], v[118:119], v[156:157] op_sel_hi:[1,0]
	v_pk_mul_f32 v[116:117], v[116:117], v[156:157] op_sel_hi:[1,0]
	v_max_f32_e32 v114, 0, v114
	v_max_f32_e32 v115, 0, v115
	global_store_dwordx4 v[140:141], v[122:125], off sc1
	v_max_f32_e32 v118, 0, v118
	v_max_f32_e32 v119, 0, v119
	v_pk_mul_f32 v[122:123], v[114:115], v[114:115]
	v_max_f32_e32 v114, 0, v120
	v_max_f32_e32 v116, 0, v116
	v_max_f32_e32 v115, 0, v121
	v_max_f32_e32 v117, 0, v117
	v_pk_mul_f32 v[118:119], v[118:119], v[118:119]
	v_pk_mul_f32 v[120:121], v[114:115], v[114:115]
	v_pk_mul_f32 v[124:125], v[116:117], v[116:117]
	v_cvt_pk_f16_f32 v114, v118, v119
	v_cvt_pk_f16_f32 v115, v120, v121
	v_cvt_pk_f16_f32 v116, v122, v123
	v_cvt_pk_f16_f32 v117, v124, v125
	global_store_dwordx4 v[140:141], v[114:117], off offset:256 sc1
	v_pk_mul_f32 v[90:91], v[90:91], v[146:147] op_sel_hi:[1,0]
	v_pk_mul_f32 v[96:97], v[96:97], v[146:147] op_sel_hi:[1,0]
	v_mov_b32_e32 v116, v157
	v_or_b32_e32 v114, 16, v148
	v_pk_mul_f32 v[106:107], v[106:107], v[116:117] op_sel_hi:[1,0]
	v_ashrrev_i32_e32 v115, 31, v114
	v_pk_mul_f32 v[112:113], v[112:113], v[116:117] op_sel_hi:[1,0]
	v_pk_mul_f32 v[110:111], v[110:111], v[116:117] op_sel_hi:[1,0]
	v_pk_mul_f32 v[108:109], v[108:109], v[116:117] op_sel_hi:[1,0]
	v_max_f32_e32 v106, 0, v106
	v_max_f32_e32 v107, 0, v107
	v_lshlrev_b64 v[114:115], 13, v[114:115]
	v_max_f32_e32 v110, 0, v110
	v_max_f32_e32 v111, 0, v111
	v_pk_mul_f32 v[118:119], v[106:107], v[106:107]
	v_max_f32_e32 v106, 0, v112
	v_max_f32_e32 v108, 0, v108
	v_max_f32_e32 v107, 0, v113
	v_max_f32_e32 v109, 0, v109
	v_lshl_add_u64 v[114:115], s[74:75], 0, v[114:115]
	v_pk_mul_f32 v[110:111], v[110:111], v[110:111]
	v_pk_mul_f32 v[112:113], v[106:107], v[106:107]
	v_pk_mul_f32 v[120:121], v[108:109], v[108:109]
	v_pk_mul_f32 v[98:99], v[98:99], v[116:117] op_sel_hi:[1,0]
	v_lshl_add_u64 v[114:115], v[114:115], 0, v[160:161]
	v_cvt_pk_f16_f32 v106, v110, v111
	v_cvt_pk_f16_f32 v107, v112, v113
	v_cvt_pk_f16_f32 v108, v118, v119
	v_cvt_pk_f16_f32 v109, v120, v121
	v_pk_mul_f32 v[104:105], v[104:105], v[116:117] op_sel_hi:[1,0]
	v_pk_mul_f32 v[102:103], v[102:103], v[116:117] op_sel_hi:[1,0]
	v_pk_mul_f32 v[100:101], v[100:101], v[116:117] op_sel_hi:[1,0]
	v_max_f32_e32 v98, 0, v98
	v_max_f32_e32 v99, 0, v99
	global_store_dwordx4 v[114:115], v[106:109], off sc1
	v_max_f32_e32 v102, 0, v102
	v_max_f32_e32 v103, 0, v103
	v_pk_mul_f32 v[106:107], v[98:99], v[98:99]
	v_max_f32_e32 v98, 0, v104
	v_max_f32_e32 v100, 0, v100
	v_max_f32_e32 v99, 0, v105
	v_max_f32_e32 v101, 0, v101
	v_pk_mul_f32 v[102:103], v[102:103], v[102:103]
	v_pk_mul_f32 v[104:105], v[98:99], v[98:99]
	v_pk_mul_f32 v[108:109], v[100:101], v[100:101]
	v_cvt_pk_f16_f32 v98, v102, v103
	v_cvt_pk_f16_f32 v99, v104, v105
	v_cvt_pk_f16_f32 v100, v106, v107
	v_cvt_pk_f16_f32 v101, v108, v109
	global_store_dwordx4 v[114:115], v[98:101], off offset:256 sc1
	v_pk_mul_f32 v[94:95], v[94:95], v[146:147] op_sel_hi:[1,0]
	v_pk_mul_f32 v[92:93], v[92:93], v[146:147] op_sel_hi:[1,0]
	v_or_b32_e32 v98, 32, v148
	v_ashrrev_i32_e32 v99, 31, v98
	v_max_f32_e32 v90, 0, v90
	v_max_f32_e32 v91, 0, v91
	v_lshlrev_b64 v[98:99], 13, v[98:99]
	v_max_f32_e32 v94, 0, v94
	v_max_f32_e32 v95, 0, v95
	v_pk_mul_f32 v[100:101], v[90:91], v[90:91]
	v_max_f32_e32 v90, 0, v96
	v_max_f32_e32 v92, 0, v92
	v_max_f32_e32 v91, 0, v97
	v_max_f32_e32 v93, 0, v93
	v_lshl_add_u64 v[98:99], s[74:75], 0, v[98:99]
	v_pk_mul_f32 v[94:95], v[94:95], v[94:95]
	v_pk_mul_f32 v[96:97], v[90:91], v[90:91]
	v_pk_mul_f32 v[102:103], v[92:93], v[92:93]
	v_pk_mul_f32 v[82:83], v[82:83], v[146:147] op_sel_hi:[1,0]
	v_lshl_add_u64 v[98:99], v[98:99], 0, v[160:161]
	v_cvt_pk_f16_f32 v90, v94, v95
	v_cvt_pk_f16_f32 v91, v96, v97
	v_cvt_pk_f16_f32 v92, v100, v101
	v_cvt_pk_f16_f32 v93, v102, v103
	v_pk_mul_f32 v[88:89], v[88:89], v[146:147] op_sel_hi:[1,0]
	v_pk_mul_f32 v[86:87], v[86:87], v[146:147] op_sel_hi:[1,0]
	v_pk_mul_f32 v[84:85], v[84:85], v[146:147] op_sel_hi:[1,0]
; __device__ __forceinline__ unsigned cvtpk(float lo, float hi) { f32x2_t v = {lo, hi}; f16x2_t b = __builtin_convertvector(v, f16x2_t); return __builtin_bit_cast(unsigned, b); }
;     __device__ __forceinline__ void operator()(const f32x4 (&acc)[2][2][4][2], const Unit& u, int wr, int wc, int fr, int fq) const {
;     ...
; #pragma unroll
;         for (int ai = 0; ai < 2; ++ai)
; #pragma unroll
;             for (int m = 0; m < 4; ++m) { const int row = row0 + ai * HALF + m * 16; bf16_t* rowp = H + (size_t)row * 4096 + col0;
; #pragma unroll
;                 for (int bj = 0; bj < 2; ++bj) { f32x4 v0 = acc[ai][bj][m][0] * rs[ai][m], v1 = acc[ai][bj][m][1] * rs[ai][m];
; #pragma unroll
;                     for (int e = 0; e < 4; ++e) { const float a = fmaxf(v0[e], 0.f), b = fmaxf(v1[e], 0.f); v0[e] = a * a; v1[e] = b * b; }
;                     u32x4 w; w.x = cvtpk(v0[0], v0[1]); w.y = cvtpk(v0[2], v0[3]); w.z = cvtpk(v1[0], v1[1]); w.w = cvtpk(v1[2], v1[3]);
;                     *(u32x4*)(rowp + bj * HALF) = w; } }
	v_max_f32_e32 v82, 0, v82
	v_max_f32_e32 v83, 0, v83
	global_store_dwordx4 v[98:99], v[90:93], off sc1
	v_max_f32_e32 v86, 0, v86
	v_max_f32_e32 v87, 0, v87
	v_pk_mul_f32 v[90:91], v[82:83], v[82:83]
	v_max_f32_e32 v82, 0, v88
	v_max_f32_e32 v84, 0, v84
	v_max_f32_e32 v83, 0, v89
	v_max_f32_e32 v85, 0, v85
	v_pk_mul_f32 v[86:87], v[86:87], v[86:87]
	v_pk_mul_f32 v[88:89], v[82:83], v[82:83]
	v_pk_mul_f32 v[92:93], v[84:85], v[84:85]
	v_cvt_pk_f16_f32 v82, v86, v87
	v_cvt_pk_f16_f32 v83, v88, v89
	v_cvt_pk_f16_f32 v84, v90, v91
	v_cvt_pk_f16_f32 v85, v92, v93
	global_store_dwordx4 v[98:99], v[82:85], off offset:256 sc1
	v_pk_mul_f32 v[62:63], v[62:63], v[144:145] op_sel_hi:[1,0]
	v_pk_mul_f32 v[58:59], v[58:59], v[144:145] op_sel_hi:[1,0]
	v_mov_b32_e32 v84, v147
	v_or_b32_e32 v82, 48, v148
	v_pk_mul_f32 v[74:75], v[74:75], v[84:85] op_sel_hi:[1,0]
	v_ashrrev_i32_e32 v83, 31, v82
	v_pk_mul_f32 v[80:81], v[80:81], v[84:85] op_sel_hi:[1,0]
	v_pk_mul_f32 v[78:79], v[78:79], v[84:85] op_sel_hi:[1,0]
	v_pk_mul_f32 v[76:77], v[76:77], v[84:85] op_sel_hi:[1,0]
	v_max_f32_e32 v74, 0, v74
	v_max_f32_e32 v75, 0, v75
	v_lshlrev_b64 v[82:83], 13, v[82:83]
	v_max_f32_e32 v78, 0, v78
	v_max_f32_e32 v79, 0, v79
	v_pk_mul_f32 v[86:87], v[74:75], v[74:75]
	v_max_f32_e32 v74, 0, v80
	v_max_f32_e32 v76, 0, v76
	v_max_f32_e32 v75, 0, v81
	v_max_f32_e32 v77, 0, v77
	v_lshl_add_u64 v[82:83], s[74:75], 0, v[82:83]
	v_pk_mul_f32 v[78:79], v[78:79], v[78:79]
	v_pk_mul_f32 v[80:81], v[74:75], v[74:75]
	v_pk_mul_f32 v[88:89], v[76:77], v[76:77]
	v_pk_mul_f32 v[66:67], v[66:67], v[84:85] op_sel_hi:[1,0]
	v_lshl_add_u64 v[82:83], v[82:83], 0, v[160:161]
	v_cvt_pk_f16_f32 v74, v78, v79
	v_cvt_pk_f16_f32 v75, v80, v81
	v_cvt_pk_f16_f32 v76, v86, v87
	v_cvt_pk_f16_f32 v77, v88, v89
	v_pk_mul_f32 v[72:73], v[72:73], v[84:85] op_sel_hi:[1,0]
	v_pk_mul_f32 v[70:71], v[70:71], v[84:85] op_sel_hi:[1,0]
	v_pk_mul_f32 v[68:69], v[68:69], v[84:85] op_sel_hi:[1,0]
	v_max_f32_e32 v66, 0, v66
	v_max_f32_e32 v67, 0, v67
	global_store_dwordx4 v[82:83], v[74:77], off sc1
	v_max_f32_e32 v70, 0, v70
	v_max_f32_e32 v71, 0, v71
	v_pk_mul_f32 v[74:75], v[66:67], v[66:67]
	v_max_f32_e32 v66, 0, v72
	v_max_f32_e32 v68, 0, v68
	v_max_f32_e32 v67, 0, v73
	v_max_f32_e32 v69, 0, v69
	v_pk_mul_f32 v[70:71], v[70:71], v[70:71]
	v_pk_mul_f32 v[72:73], v[66:67], v[66:67]
	v_pk_mul_f32 v[76:77], v[68:69], v[68:69]
	v_cvt_pk_f16_f32 v66, v70, v71
	v_cvt_pk_f16_f32 v67, v72, v73
	v_cvt_pk_f16_f32 v68, v74, v75
	v_cvt_pk_f16_f32 v69, v76, v77
	v_pk_mul_f32 v[64:65], v[64:65], v[144:145] op_sel_hi:[1,0]
	v_pk_mul_f32 v[60:61], v[60:61], v[144:145] op_sel_hi:[1,0]
	v_max_f32_e32 v62, 0, v62
	v_max_f32_e32 v58, 0, v58
	v_max_f32_e32 v63, 0, v63
	v_max_f32_e32 v59, 0, v59
	global_store_dwordx4 v[82:83], v[66:69], off offset:256 sc1
	v_pk_mul_f32 v[62:63], v[62:63], v[62:63]
	v_max_f32_e32 v60, 0, v60
	v_pk_mul_f32 v[68:69], v[58:59], v[58:59]
	v_max_f32_e32 v58, 0, v64
	v_max_f32_e32 v59, 0, v65
	v_max_f32_e32 v61, 0, v61
	s_mov_b32 s21, 0x100000
	v_pk_mul_f32 v[64:65], v[58:59], v[58:59]
	v_pk_mul_f32 v[70:71], v[60:61], v[60:61]
	v_cvt_pk_f16_f32 v58, v62, v63
	v_add_co_u32_e32 v62, vcc, s21, v140
	v_pk_mul_f32 v[50:51], v[50:51], v[144:145] op_sel_hi:[1,0]
	v_cvt_pk_f16_f32 v59, v64, v65
	v_cvt_pk_f16_f32 v60, v68, v69
	v_cvt_pk_f16_f32 v61, v70, v71
	v_addc_co_u32_e32 v63, vcc, 0, v141, vcc
	v_pk_mul_f32 v[56:57], v[56:57], v[144:145] op_sel_hi:[1,0]
	v_pk_mul_f32 v[54:55], v[54:55], v[144:145] op_sel_hi:[1,0]
	v_pk_mul_f32 v[52:53], v[52:53], v[144:145] op_sel_hi:[1,0]
	v_max_f32_e32 v50, 0, v50
	v_max_f32_e32 v51, 0, v51
	global_store_dwordx4 v[62:63], v[58:61], off sc1
	v_max_f32_e32 v54, 0, v54
	v_max_f32_e32 v55, 0, v55
	v_pk_mul_f32 v[58:59], v[50:51], v[50:51]
	v_max_f32_e32 v50, 0, v56
	v_max_f32_e32 v52, 0, v52
	v_max_f32_e32 v51, 0, v57
	v_max_f32_e32 v53, 0, v53
	s_mov_b64 s[26:27], 0x100000
	v_pk_mul_f32 v[54:55], v[54:55], v[54:55]
	v_pk_mul_f32 v[56:57], v[50:51], v[50:51]
	v_pk_mul_f32 v[60:61], v[52:53], v[52:53]
	v_lshl_add_u64 v[66:67], v[140:141], 0, s[26:27]
	v_cvt_pk_f16_f32 v50, v54, v55
	v_cvt_pk_f16_f32 v51, v56, v57
	v_cvt_pk_f16_f32 v52, v58, v59
	v_cvt_pk_f16_f32 v53, v60, v61
	global_store_dwordx4 v[66:67], v[50:53], off offset:256 sc1
	s_mov_b32 s21, 0x120000
	s_mov_b64 s[26:27], 0x120000
	v_mov_b32_e32 v52, v145
	v_pk_mul_f32 v[46:47], v[46:47], v[52:53] op_sel_hi:[1,0]
	v_pk_mul_f32 v[42:43], v[42:43], v[52:53] op_sel_hi:[1,0]
	v_pk_mul_f32 v[48:49], v[48:49], v[52:53] op_sel_hi:[1,0]
	v_pk_mul_f32 v[44:45], v[44:45], v[52:53] op_sel_hi:[1,0]
	v_max_f32_e32 v46, 0, v46
	v_max_f32_e32 v42, 0, v42
	v_max_f32_e32 v47, 0, v47
	v_max_f32_e32 v43, 0, v43
	v_pk_mul_f32 v[46:47], v[46:47], v[46:47]
	v_pk_mul_f32 v[54:55], v[42:43], v[42:43]
	v_max_f32_e32 v42, 0, v48
	v_max_f32_e32 v44, 0, v44
	v_max_f32_e32 v43, 0, v49
	v_max_f32_e32 v45, 0, v45
	v_pk_mul_f32 v[48:49], v[42:43], v[42:43]
	v_pk_mul_f32 v[56:57], v[44:45], v[44:45]
	v_cvt_pk_f16_f32 v42, v46, v47
; __device__ __forceinline__ unsigned cvtpk(float lo, float hi) { f32x2_t v = {lo, hi}; f16x2_t b = __builtin_convertvector(v, f16x2_t); return __builtin_bit_cast(unsigned, b); }
; #define PG8_BAR __builtin_amdgcn_s_barrier()
;     __device__ __forceinline__ void operator()(const f32x4 (&acc)[2][2][4][2], const Unit& u, int wr, int wc, int fr, int fq) const {
;     ...
; #pragma unroll
;         for (int ai = 0; ai < 2; ++ai)
; #pragma unroll
;             for (int m = 0; m < 4; ++m) { const int row = row0 + ai * HALF + m * 16; bf16_t* rowp = H + (size_t)row * 4096 + col0;
; #pragma unroll
;                 for (int bj = 0; bj < 2; ++bj) { f32x4 v0 = acc[ai][bj][m][0] * rs[ai][m], v1 = acc[ai][bj][m][1] * rs[ai][m];
; #pragma unroll
;                     for (int e = 0; e < 4; ++e) { const float a = fmaxf(v0[e], 0.f), b = fmaxf(v1[e], 0.f); v0[e] = a * a; v1[e] = b * b; }
;                     u32x4 w; w.x = cvtpk(v0[0], v0[1]); w.y = cvtpk(v0[2], v0[3]); w.z = cvtpk(v1[0], v1[1]); w.w = cvtpk(v1[2], v1[3]);
;                     *(u32x4*)(rowp + bj * HALF) = w; } }
; template <class Epi, class Sched, bool ALIGN_EPI = false, bool SP2 = false>
; __device__ __forceinline__ void gemm_phase(PG8_LAS unsigned char* lds, const Gemm g, const Sched& S, const Epi& E) {
;     ...
;         if (!has_next) break;
; #pragma unroll
;         for (int a = 0; a < 2; ++a)
; #pragma unroll
;             for (int b = 0; b < 2; ++b)
; #pragma unroll
;                 for (int m = 0; m < 4; ++m)
; #pragma unroll
;                     for (int n = 0; n < 2; ++n) acc[a][b][m][n] = (f32x4){0.f, 0.f, 0.f, 0.f};
;         cur = nxt; cA = nA; cB = nB; ++ui;
;         if constexpr (ALIGN_EPI) { if (wr == 1) PG8_BAR; }
	v_add_co_u32_e32 v46, vcc, s21, v140
	v_pk_mul_f32 v[34:35], v[34:35], v[52:53] op_sel_hi:[1,0]
	v_cvt_pk_f16_f32 v43, v48, v49
	v_cvt_pk_f16_f32 v44, v54, v55
	v_cvt_pk_f16_f32 v45, v56, v57
	v_addc_co_u32_e32 v47, vcc, 0, v141, vcc
	v_pk_mul_f32 v[40:41], v[40:41], v[52:53] op_sel_hi:[1,0]
	v_pk_mul_f32 v[38:39], v[38:39], v[52:53] op_sel_hi:[1,0]
	v_pk_mul_f32 v[36:37], v[36:37], v[52:53] op_sel_hi:[1,0]
	v_max_f32_e32 v34, 0, v34
	v_max_f32_e32 v35, 0, v35
	global_store_dwordx4 v[46:47], v[42:45], off sc1
	v_max_f32_e32 v38, 0, v38
	v_max_f32_e32 v39, 0, v39
	v_pk_mul_f32 v[42:43], v[34:35], v[34:35]
	v_max_f32_e32 v34, 0, v40
	v_max_f32_e32 v36, 0, v36
	v_max_f32_e32 v35, 0, v41
	v_max_f32_e32 v37, 0, v37
	v_pk_mul_f32 v[38:39], v[38:39], v[38:39]
	v_pk_mul_f32 v[40:41], v[34:35], v[34:35]
	v_pk_mul_f32 v[44:45], v[36:37], v[36:37]
	v_pk_mul_f32 v[30:31], v[30:31], v[142:143] op_sel_hi:[1,0]
	v_pk_mul_f32 v[26:27], v[26:27], v[142:143] op_sel_hi:[1,0]
	v_lshl_add_u64 v[50:51], v[140:141], 0, s[26:27]
	v_cvt_pk_f16_f32 v34, v38, v39
	v_cvt_pk_f16_f32 v35, v40, v41
	v_cvt_pk_f16_f32 v36, v42, v43
	v_cvt_pk_f16_f32 v37, v44, v45
	v_pk_mul_f32 v[32:33], v[32:33], v[142:143] op_sel_hi:[1,0]
	v_pk_mul_f32 v[28:29], v[28:29], v[142:143] op_sel_hi:[1,0]
	v_max_f32_e32 v30, 0, v30
	v_max_f32_e32 v26, 0, v26
	v_max_f32_e32 v31, 0, v31
	v_max_f32_e32 v27, 0, v27
	global_store_dwordx4 v[50:51], v[34:37], off offset:256 sc1
	v_pk_mul_f32 v[30:31], v[30:31], v[30:31]
	v_max_f32_e32 v28, 0, v28
	v_pk_mul_f32 v[36:37], v[26:27], v[26:27]
	v_max_f32_e32 v26, 0, v32
	v_max_f32_e32 v27, 0, v33
	v_max_f32_e32 v29, 0, v29
	s_mov_b32 s21, 0x140000
	v_pk_mul_f32 v[32:33], v[26:27], v[26:27]
	v_pk_mul_f32 v[38:39], v[28:29], v[28:29]
	v_cvt_pk_f16_f32 v26, v30, v31
	v_add_co_u32_e32 v30, vcc, s21, v140
	v_pk_mul_f32 v[18:19], v[18:19], v[142:143] op_sel_hi:[1,0]
	v_cvt_pk_f16_f32 v27, v32, v33
	v_cvt_pk_f16_f32 v28, v36, v37
	v_cvt_pk_f16_f32 v29, v38, v39
	v_addc_co_u32_e32 v31, vcc, 0, v141, vcc
	v_pk_mul_f32 v[24:25], v[24:25], v[142:143] op_sel_hi:[1,0]
	v_pk_mul_f32 v[22:23], v[22:23], v[142:143] op_sel_hi:[1,0]
	v_pk_mul_f32 v[20:21], v[20:21], v[142:143] op_sel_hi:[1,0]
	v_max_f32_e32 v18, 0, v18
	v_max_f32_e32 v19, 0, v19
	global_store_dwordx4 v[30:31], v[26:29], off sc1
	v_max_f32_e32 v22, 0, v22
	v_max_f32_e32 v23, 0, v23
	v_pk_mul_f32 v[26:27], v[18:19], v[18:19]
	v_max_f32_e32 v18, 0, v24
	v_max_f32_e32 v20, 0, v20
	v_max_f32_e32 v19, 0, v25
	v_max_f32_e32 v21, 0, v21
	s_mov_b64 s[26:27], 0x140000
	v_pk_mul_f32 v[22:23], v[22:23], v[22:23]
	v_pk_mul_f32 v[24:25], v[18:19], v[18:19]
	v_pk_mul_f32 v[28:29], v[20:21], v[20:21]
	v_lshl_add_u64 v[34:35], v[140:141], 0, s[26:27]
	v_cvt_pk_f16_f32 v18, v22, v23
	v_cvt_pk_f16_f32 v19, v24, v25
	v_cvt_pk_f16_f32 v20, v26, v27
	v_cvt_pk_f16_f32 v21, v28, v29
	global_store_dwordx4 v[34:35], v[18:21], off offset:256 sc1
	s_mov_b32 s21, 0x160000
	s_mov_b64 s[26:27], 0x160000
	v_mov_b32_e32 v20, v143
	v_pk_mul_f32 v[14:15], v[14:15], v[20:21] op_sel_hi:[1,0]
	v_pk_mul_f32 v[10:11], v[10:11], v[20:21] op_sel_hi:[1,0]
	v_pk_mul_f32 v[16:17], v[16:17], v[20:21] op_sel_hi:[1,0]
	v_pk_mul_f32 v[12:13], v[12:13], v[20:21] op_sel_hi:[1,0]
	v_max_f32_e32 v14, 0, v14
	v_max_f32_e32 v10, 0, v10
	v_max_f32_e32 v15, 0, v15
	v_max_f32_e32 v11, 0, v11
	v_pk_mul_f32 v[14:15], v[14:15], v[14:15]
	v_pk_mul_f32 v[22:23], v[10:11], v[10:11]
	v_max_f32_e32 v10, 0, v16
	v_max_f32_e32 v12, 0, v12
	v_max_f32_e32 v11, 0, v17
	v_max_f32_e32 v13, 0, v13
	v_pk_mul_f32 v[16:17], v[10:11], v[10:11]
	v_pk_mul_f32 v[24:25], v[12:13], v[12:13]
	v_cvt_pk_f16_f32 v10, v14, v15
	v_add_co_u32_e32 v14, vcc, s21, v140
	v_pk_mul_f32 v[2:3], v[2:3], v[20:21] op_sel_hi:[1,0]
	v_cvt_pk_f16_f32 v11, v16, v17
	v_cvt_pk_f16_f32 v12, v22, v23
	v_cvt_pk_f16_f32 v13, v24, v25
	v_addc_co_u32_e32 v15, vcc, 0, v141, vcc
	v_pk_mul_f32 v[8:9], v[8:9], v[20:21] op_sel_hi:[1,0]
	v_pk_mul_f32 v[6:7], v[6:7], v[20:21] op_sel_hi:[1,0]
	v_pk_mul_f32 v[4:5], v[4:5], v[20:21] op_sel_hi:[1,0]
	v_max_f32_e32 v2, 0, v2
	v_max_f32_e32 v3, 0, v3
	global_store_dwordx4 v[14:15], v[10:13], off sc1
	v_max_f32_e32 v6, 0, v6
	v_max_f32_e32 v7, 0, v7
	v_pk_mul_f32 v[10:11], v[2:3], v[2:3]
	v_max_f32_e32 v2, 0, v8
	v_max_f32_e32 v4, 0, v4
	v_max_f32_e32 v3, 0, v9
	v_max_f32_e32 v5, 0, v5
	v_pk_mul_f32 v[6:7], v[6:7], v[6:7]
	v_pk_mul_f32 v[8:9], v[2:3], v[2:3]
	v_pk_mul_f32 v[12:13], v[4:5], v[4:5]
	v_readlane_b32 s76, v253, 5
	v_lshl_add_u64 v[18:19], v[140:141], 0, s[26:27]
	v_cvt_pk_f16_f32 v2, v6, v7
	v_cvt_pk_f16_f32 v3, v8, v9
	v_cvt_pk_f16_f32 v4, v10, v11
	v_cvt_pk_f16_f32 v5, v12, v13
	s_andn2_b64 vcc, exec, s[38:39]
	s_mov_b64 s[26:27], -1
	v_readlane_b32 s77, v253, 6
	v_readlane_b32 s78, v253, 7
	v_readlane_b32 s79, v253, 8
	s_mov_b32 s72, s93
	s_mov_b32 s93, s16
	global_store_dwordx4 v[18:19], v[2:5], off offset:256
	s_cbranch_vccnz .LBB0_959
	s_andn2_b64 vcc, exec, s[0:1]
	s_cbranch_vccnz .LBB0_958
	s_barrier
	s_branch .LBB0_958
